# v6 + delete the redundant s_waitcnt lgkmcnt(0) after s_setprio 1 at the head of each MFMA block
# baseline (speedup 1.0000x reference)
.LBB0_295:
	ds_read_b128 v[146:149], v155
	ds_read_b128 v[160:163], v155 offset:1024
	ds_read_b128 v[164:167], v155 offset:2048
	ds_read_b128 v[168:171], v155 offset:3072
	ds_read_b128 v[172:175], v156
	ds_read_b128 v[176:179], v156 offset:1024
	ds_read_b128 v[180:183], v156 offset:2048
	ds_read_b128 v[184:187], v156 offset:3072
	s_add_u32 s23, s64, 0xfffc0080
	s_addc_u32 s33, s65, -1
	s_cmp_eq_u32 s92, 12
	s_cselect_b32 s73, s20, s33
	s_cselect_b32 s72, s21, s23
	s_cselect_b32 s71, s19, s91
	s_cselect_b32 s70, s55, s90
	v_lshl_add_u64 v[150:151], s[64:65], 0, v[138:139]
	s_add_i32 m0, s76, 0xc000
	ds_read_b128 v[188:191], v157
	ds_read_b128 v[192:195], v157 offset:1024
	ds_read_b128 v[196:199], v157 offset:2048
	ds_read_b128 v[200:203], v157 offset:3072
	ds_read_b128 v[204:207], v157 offset:4096
	ds_read_b128 v[208:211], v157 offset:5120
	ds_read_b128 v[212:215], v157 offset:6144
	ds_read_b128 v[216:219], v157 offset:7168
	global_load_lds_dwordx4 v[150:151], off
	v_lshl_add_u64 v[150:151], s[64:65], 0, v[140:141]
	s_add_i32 m0, s76, 0xe000
	s_nop 0
	global_load_lds_dwordx4 v[150:151], off
	s_waitcnt vmcnt(8)
	s_waitcnt lgkmcnt(0)
	s_barrier
	s_setprio 1
	v_mfma_f32_16x16x32_bf16 v[124:127], v[146:149], v[188:191], v[124:127]
	v_mfma_f32_16x16x32_bf16 v[120:123], v[164:167], v[188:191], v[120:123]
	v_mfma_f32_16x16x32_bf16 v[108:111], v[146:149], v[196:199], v[108:111]
	v_mfma_f32_16x16x32_bf16 v[104:107], v[164:167], v[196:199], v[104:107]
	v_mfma_f32_16x16x32_bf16 v[92:95], v[146:149], v[204:207], v[92:95]
	v_mfma_f32_16x16x32_bf16 v[88:91], v[164:167], v[204:207], v[88:91]
	v_mfma_f32_16x16x32_bf16 v[76:79], v[146:149], v[212:215], v[76:79]
	v_mfma_f32_16x16x32_bf16 v[72:75], v[164:167], v[212:215], v[72:75]
	v_mfma_f32_16x16x32_bf16 v[124:127], v[160:163], v[192:195], v[124:127]
	v_mfma_f32_16x16x32_bf16 v[120:123], v[168:171], v[192:195], v[120:123]
	v_mfma_f32_16x16x32_bf16 v[108:111], v[160:163], v[200:203], v[108:111]
	v_mfma_f32_16x16x32_bf16 v[104:107], v[168:171], v[200:203], v[104:107]
	v_mfma_f32_16x16x32_bf16 v[92:95], v[160:163], v[208:211], v[92:95]
	v_mfma_f32_16x16x32_bf16 v[88:91], v[168:171], v[208:211], v[88:91]
	v_mfma_f32_16x16x32_bf16 v[76:79], v[160:163], v[216:219], v[76:79]
	v_mfma_f32_16x16x32_bf16 v[72:75], v[168:171], v[216:219], v[72:75]
	v_mfma_f32_16x16x32_bf16 v[116:119], v[172:175], v[188:191], v[116:119]
	v_mfma_f32_16x16x32_bf16 v[112:115], v[180:183], v[188:191], v[112:115]
	v_mfma_f32_16x16x32_bf16 v[100:103], v[172:175], v[196:199], v[100:103]
	v_mfma_f32_16x16x32_bf16 v[96:99], v[180:183], v[196:199], v[96:99]
	v_mfma_f32_16x16x32_bf16 v[84:87], v[172:175], v[204:207], v[84:87]
	v_mfma_f32_16x16x32_bf16 v[80:83], v[180:183], v[204:207], v[80:83]
	v_mfma_f32_16x16x32_bf16 v[68:71], v[172:175], v[212:215], v[68:71]
	v_mfma_f32_16x16x32_bf16 v[64:67], v[180:183], v[212:215], v[64:67]
	v_mfma_f32_16x16x32_bf16 v[116:119], v[176:179], v[192:195], v[116:119]
	v_mfma_f32_16x16x32_bf16 v[112:115], v[184:187], v[192:195], v[112:115]
	v_mfma_f32_16x16x32_bf16 v[100:103], v[176:179], v[200:203], v[100:103]
	v_mfma_f32_16x16x32_bf16 v[96:99], v[184:187], v[200:203], v[96:99]
	v_mfma_f32_16x16x32_bf16 v[84:87], v[176:179], v[208:211], v[84:87]
	v_mfma_f32_16x16x32_bf16 v[80:83], v[184:187], v[208:211], v[80:83]
	v_mfma_f32_16x16x32_bf16 v[68:71], v[176:179], v[216:219], v[68:71]
	v_mfma_f32_16x16x32_bf16 v[64:67], v[184:187], v[216:219], v[64:67]
	s_setprio 0
	s_barrier
	s_add_i32 s23, s85, s74
	v_lshl_add_u64 v[150:151], s[70:71], 0, v[132:133]
	s_mov_b32 m0, s23
	ds_read_b128 v[188:191], v157 offset:16384
	ds_read_b128 v[192:195], v157 offset:17408
	ds_read_b128 v[196:199], v157 offset:18432
	ds_read_b128 v[200:203], v157 offset:19456
	ds_read_b128 v[204:207], v157 offset:20480
	ds_read_b128 v[208:211], v157 offset:21504
	ds_read_b128 v[212:215], v157 offset:22528
	ds_read_b128 v[216:219], v157 offset:23552
	global_load_lds_dwordx4 v[150:151], off
	s_add_i32 m0, s23, 0x2000
	s_add_u32 s94, s70, 0x40000
	v_lshl_add_u64 v[220:221], s[70:71], 0, v[136:137]
	s_addc_u32 s95, s71, 0
	s_add_i32 s23, s86, s74
	global_load_lds_dwordx4 v[220:221], off
	v_lshl_add_u64 v[222:223], s[94:95], 0, v[132:133]
	s_mov_b32 m0, s23
	v_lshl_add_u64 v[224:225], s[72:73], 0, v[134:135]
	global_load_lds_dwordx4 v[222:223], off
	v_lshl_add_u64 v[222:223], s[94:95], 0, v[136:137]
	s_add_i32 m0, s23, 0x2000
	s_nop 0
	global_load_lds_dwordx4 v[222:223], off
	v_lshl_add_u64 v[222:223], s[72:73], 0, v[130:131]
	s_mov_b32 m0, s76
	s_nop 0
	global_load_lds_dwordx4 v[222:223], off
	s_mov_b32 m0, s77
	s_nop 0
	global_load_lds_dwordx4 v[224:225], off
	s_waitcnt vmcnt(8)
	s_waitcnt lgkmcnt(0)
	s_barrier
	s_setprio 1
	v_mfma_f32_16x16x32_bf16 v[60:63], v[146:149], v[188:191], v[60:63]
	v_mfma_f32_16x16x32_bf16 v[56:59], v[164:167], v[188:191], v[56:59]
	v_mfma_f32_16x16x32_bf16 v[44:47], v[146:149], v[196:199], v[44:47]
	v_mfma_f32_16x16x32_bf16 v[40:43], v[164:167], v[196:199], v[40:43]
	v_mfma_f32_16x16x32_bf16 v[28:31], v[146:149], v[204:207], v[28:31]
	v_mfma_f32_16x16x32_bf16 v[24:27], v[164:167], v[204:207], v[24:27]
	v_mfma_f32_16x16x32_bf16 v[12:15], v[146:149], v[212:215], v[12:15]
	v_mfma_f32_16x16x32_bf16 v[8:11], v[164:167], v[212:215], v[8:11]
	v_mfma_f32_16x16x32_bf16 v[60:63], v[160:163], v[192:195], v[60:63]
	v_mfma_f32_16x16x32_bf16 v[56:59], v[168:171], v[192:195], v[56:59]
	v_mfma_f32_16x16x32_bf16 v[44:47], v[160:163], v[200:203], v[44:47]
	v_mfma_f32_16x16x32_bf16 v[40:43], v[168:171], v[200:203], v[40:43]
	v_mfma_f32_16x16x32_bf16 v[28:31], v[160:163], v[208:211], v[28:31]
	v_mfma_f32_16x16x32_bf16 v[24:27], v[168:171], v[208:211], v[24:27]
	v_mfma_f32_16x16x32_bf16 v[12:15], v[160:163], v[216:219], v[12:15]
	v_mfma_f32_16x16x32_bf16 v[8:11], v[168:171], v[216:219], v[8:11]
	v_mfma_f32_16x16x32_bf16 v[52:55], v[172:175], v[188:191], v[52:55]
	v_mfma_f32_16x16x32_bf16 v[48:51], v[180:183], v[188:191], v[48:51]
	v_mfma_f32_16x16x32_bf16 v[36:39], v[172:175], v[196:199], v[36:39]
	v_mfma_f32_16x16x32_bf16 v[32:35], v[180:183], v[196:199], v[32:35]
	v_mfma_f32_16x16x32_bf16 v[20:23], v[172:175], v[204:207], v[20:23]
	v_mfma_f32_16x16x32_bf16 v[16:19], v[180:183], v[204:207], v[16:19]
	v_mfma_f32_16x16x32_bf16 v[4:7], v[172:175], v[212:215], v[4:7]
	v_mfma_f32_16x16x32_bf16 v[0:3], v[180:183], v[212:215], v[0:3]
	v_mfma_f32_16x16x32_bf16 v[52:55], v[176:179], v[192:195], v[52:55]
	v_mfma_f32_16x16x32_bf16 v[48:51], v[184:187], v[192:195], v[48:51]
	v_mfma_f32_16x16x32_bf16 v[36:39], v[176:179], v[200:203], v[36:39]
	v_mfma_f32_16x16x32_bf16 v[32:35], v[184:187], v[200:203], v[32:35]
	v_mfma_f32_16x16x32_bf16 v[20:23], v[176:179], v[208:211], v[20:23]
	v_mfma_f32_16x16x32_bf16 v[16:19], v[184:187], v[208:211], v[16:19]
	v_mfma_f32_16x16x32_bf16 v[4:7], v[176:179], v[216:219], v[4:7]
	v_mfma_f32_16x16x32_bf16 v[0:3], v[184:187], v[216:219], v[0:3]
	s_setprio 0
	s_barrier
	s_add_i32 s23, 0, 0x18000
	v_add_u32_e32 v159, s23, v153
	s_add_i32 s33, 0, 0x1c000
	ds_read_b128 v[146:149], v159
	ds_read_b128 v[160:163], v159 offset:1024
	ds_read_b128 v[164:167], v159 offset:2048
	ds_read_b128 v[168:171], v159 offset:3072
	v_add_u32_e32 v159, s33, v153
	ds_read_b128 v[172:175], v159
	ds_read_b128 v[176:179], v159 offset:1024
	ds_read_b128 v[180:183], v159 offset:2048
	ds_read_b128 v[184:187], v159 offset:3072
	s_add_u32 s72, s72, 0x40000
	s_addc_u32 s73, s73, 0
	s_mov_b32 m0, s78
	v_lshl_add_u64 v[226:227], s[72:73], 0, v[130:131]
	ds_read_b128 v[188:191], v157 offset:32768
	ds_read_b128 v[192:195], v157 offset:33792
	ds_read_b128 v[196:199], v157 offset:34816
	ds_read_b128 v[200:203], v157 offset:35840
	ds_read_b128 v[204:207], v157 offset:36864
	ds_read_b128 v[208:211], v157 offset:37888
	ds_read_b128 v[212:215], v157 offset:38912
	ds_read_b128 v[216:219], v157 offset:39936
	global_load_lds_dwordx4 v[226:227], off
	v_lshl_add_u64 v[226:227], s[72:73], 0, v[134:135]
	s_mov_b32 m0, s79
	s_nop 0
	global_load_lds_dwordx4 v[226:227], off
	s_waitcnt vmcnt(8)
	s_waitcnt lgkmcnt(0)
	s_barrier
	s_setprio 1
	v_mfma_f32_16x16x32_bf16 v[124:127], v[146:149], v[188:191], v[124:127]
	v_mfma_f32_16x16x32_bf16 v[120:123], v[164:167], v[188:191], v[120:123]
	v_mfma_f32_16x16x32_bf16 v[108:111], v[146:149], v[196:199], v[108:111]
	v_mfma_f32_16x16x32_bf16 v[104:107], v[164:167], v[196:199], v[104:107]
	v_mfma_f32_16x16x32_bf16 v[92:95], v[146:149], v[204:207], v[92:95]
	v_mfma_f32_16x16x32_bf16 v[88:91], v[164:167], v[204:207], v[88:91]
	v_mfma_f32_16x16x32_bf16 v[76:79], v[146:149], v[212:215], v[76:79]
	v_mfma_f32_16x16x32_bf16 v[72:75], v[164:167], v[212:215], v[72:75]
	v_mfma_f32_16x16x32_bf16 v[124:127], v[160:163], v[192:195], v[124:127]
	v_mfma_f32_16x16x32_bf16 v[120:123], v[168:171], v[192:195], v[120:123]
	v_mfma_f32_16x16x32_bf16 v[108:111], v[160:163], v[200:203], v[108:111]
	v_mfma_f32_16x16x32_bf16 v[104:107], v[168:171], v[200:203], v[104:107]
	v_mfma_f32_16x16x32_bf16 v[92:95], v[160:163], v[208:211], v[92:95]
	v_mfma_f32_16x16x32_bf16 v[88:91], v[168:171], v[208:211], v[88:91]
	v_mfma_f32_16x16x32_bf16 v[76:79], v[160:163], v[216:219], v[76:79]
	v_mfma_f32_16x16x32_bf16 v[72:75], v[168:171], v[216:219], v[72:75]
	v_mfma_f32_16x16x32_bf16 v[116:119], v[172:175], v[188:191], v[116:119]
	v_mfma_f32_16x16x32_bf16 v[112:115], v[180:183], v[188:191], v[112:115]
	v_mfma_f32_16x16x32_bf16 v[100:103], v[172:175], v[196:199], v[100:103]
	v_mfma_f32_16x16x32_bf16 v[96:99], v[180:183], v[196:199], v[96:99]
	v_mfma_f32_16x16x32_bf16 v[84:87], v[172:175], v[204:207], v[84:87]
	v_mfma_f32_16x16x32_bf16 v[80:83], v[180:183], v[204:207], v[80:83]
	v_mfma_f32_16x16x32_bf16 v[68:71], v[172:175], v[212:215], v[68:71]
	v_mfma_f32_16x16x32_bf16 v[64:67], v[180:183], v[212:215], v[64:67]
	v_mfma_f32_16x16x32_bf16 v[116:119], v[176:179], v[192:195], v[116:119]
	v_mfma_f32_16x16x32_bf16 v[112:115], v[184:187], v[192:195], v[112:115]
	v_mfma_f32_16x16x32_bf16 v[100:103], v[176:179], v[200:203], v[100:103]
	v_mfma_f32_16x16x32_bf16 v[96:99], v[184:187], v[200:203], v[96:99]
	v_mfma_f32_16x16x32_bf16 v[84:87], v[176:179], v[208:211], v[84:87]
	v_mfma_f32_16x16x32_bf16 v[80:83], v[184:187], v[208:211], v[80:83]
	v_mfma_f32_16x16x32_bf16 v[68:71], v[176:179], v[216:219], v[68:71]
	v_mfma_f32_16x16x32_bf16 v[64:67], v[184:187], v[216:219], v[64:67]
	s_setprio 0
	s_barrier
	s_add_i32 s23, s23, s74
	v_lshl_add_u64 v[150:151], v[150:151], 0, s[10:11]
	s_mov_b32 m0, s23
	ds_read_b128 v[188:191], v157 offset:49152
	ds_read_b128 v[192:195], v157 offset:50176
	ds_read_b128 v[196:199], v157 offset:51200
	ds_read_b128 v[200:203], v157 offset:52224
	ds_read_b128 v[204:207], v157 offset:53248
	ds_read_b128 v[208:211], v157 offset:54272
	ds_read_b128 v[212:215], v157 offset:55296
	ds_read_b128 v[216:219], v157 offset:56320
	global_load_lds_dwordx4 v[150:151], off
	s_add_i32 m0, s23, 0x2000
	s_add_u32 s70, s70, 0x40080
	v_lshl_add_u64 v[150:151], v[220:221], 0, s[10:11]
	s_addc_u32 s71, s71, 0
	s_add_i32 s23, s33, s74
	global_load_lds_dwordx4 v[150:151], off
	v_lshl_add_u64 v[150:151], s[70:71], 0, v[132:133]
	s_mov_b32 m0, s23
	s_nop 0
	global_load_lds_dwordx4 v[150:151], off
	v_lshl_add_u64 v[150:151], s[70:71], 0, v[136:137]
	s_add_i32 m0, s23, 0x2000
	s_nop 0
	global_load_lds_dwordx4 v[150:151], off
	v_lshl_add_u64 v[150:151], v[222:223], 0, s[10:11]
	s_mov_b32 m0, s82
	s_nop 0
	global_load_lds_dwordx4 v[150:151], off
	v_lshl_add_u64 v[150:151], v[224:225], 0, s[10:11]
	s_mov_b32 m0, s83
	s_nop 0
	global_load_lds_dwordx4 v[150:151], off
	s_waitcnt vmcnt(8)
	s_waitcnt lgkmcnt(0)
	s_barrier
	s_setprio 1
	v_mfma_f32_16x16x32_bf16 v[60:63], v[146:149], v[188:191], v[60:63]
	v_mfma_f32_16x16x32_bf16 v[56:59], v[164:167], v[188:191], v[56:59]
	v_mfma_f32_16x16x32_bf16 v[44:47], v[146:149], v[196:199], v[44:47]
	v_mfma_f32_16x16x32_bf16 v[40:43], v[164:167], v[196:199], v[40:43]
	v_mfma_f32_16x16x32_bf16 v[28:31], v[146:149], v[204:207], v[28:31]
	v_mfma_f32_16x16x32_bf16 v[24:27], v[164:167], v[204:207], v[24:27]
	v_mfma_f32_16x16x32_bf16 v[12:15], v[146:149], v[212:215], v[12:15]
	v_mfma_f32_16x16x32_bf16 v[8:11], v[164:167], v[212:215], v[8:11]
	v_mfma_f32_16x16x32_bf16 v[60:63], v[160:163], v[192:195], v[60:63]
	v_mfma_f32_16x16x32_bf16 v[56:59], v[168:171], v[192:195], v[56:59]
	v_mfma_f32_16x16x32_bf16 v[44:47], v[160:163], v[200:203], v[44:47]
	v_mfma_f32_16x16x32_bf16 v[40:43], v[168:171], v[200:203], v[40:43]
	v_mfma_f32_16x16x32_bf16 v[28:31], v[160:163], v[208:211], v[28:31]
	v_mfma_f32_16x16x32_bf16 v[24:27], v[168:171], v[208:211], v[24:27]
	v_mfma_f32_16x16x32_bf16 v[12:15], v[160:163], v[216:219], v[12:15]
	v_mfma_f32_16x16x32_bf16 v[8:11], v[168:171], v[216:219], v[8:11]
	v_mfma_f32_16x16x32_bf16 v[52:55], v[172:175], v[188:191], v[52:55]
	v_mfma_f32_16x16x32_bf16 v[48:51], v[180:183], v[188:191], v[48:51]
	v_mfma_f32_16x16x32_bf16 v[36:39], v[172:175], v[196:199], v[36:39]
	v_mfma_f32_16x16x32_bf16 v[32:35], v[180:183], v[196:199], v[32:35]
	v_mfma_f32_16x16x32_bf16 v[20:23], v[172:175], v[204:207], v[20:23]
	v_mfma_f32_16x16x32_bf16 v[16:19], v[180:183], v[204:207], v[16:19]
	v_mfma_f32_16x16x32_bf16 v[4:7], v[172:175], v[212:215], v[4:7]
	v_mfma_f32_16x16x32_bf16 v[0:3], v[180:183], v[212:215], v[0:3]
	v_mfma_f32_16x16x32_bf16 v[52:55], v[176:179], v[192:195], v[52:55]
	v_mfma_f32_16x16x32_bf16 v[48:51], v[184:187], v[192:195], v[48:51]
	v_mfma_f32_16x16x32_bf16 v[36:39], v[176:179], v[200:203], v[36:39]
	v_mfma_f32_16x16x32_bf16 v[32:35], v[184:187], v[200:203], v[32:35]
	v_mfma_f32_16x16x32_bf16 v[20:23], v[176:179], v[208:211], v[20:23]
	v_mfma_f32_16x16x32_bf16 v[16:19], v[184:187], v[208:211], v[16:19]
	v_mfma_f32_16x16x32_bf16 v[4:7], v[176:179], v[216:219], v[4:7]
	v_mfma_f32_16x16x32_bf16 v[0:3], v[184:187], v[216:219], v[0:3]
	s_setprio 0
	s_barrier
	s_add_i32 s92, s92, 2
	s_add_u32 s64, s64, 0x100
	s_addc_u32 s65, s65, 0
	s_add_u32 s90, s90, 0x100
	s_addc_u32 s91, s91, 0
	s_cmp_gt_u32 s92, 13
	s_cbranch_scc0 .LBB0_295
	s_and_b64 vcc, exec, s[14:15]
	s_cbranch_vccz .LBB0_298
	s_barrier

.LBB0_437:
	ds_read_b128 v[146:149], v139
	ds_read_b128 v[150:153], v139 offset:1024
	ds_read_b128 v[154:157], v139 offset:2048
	ds_read_b128 v[158:161], v139 offset:3072
	ds_read_b128 v[162:165], v141
	ds_read_b128 v[166:169], v141 offset:1024
	ds_read_b128 v[170:173], v141 offset:2048
	ds_read_b128 v[174:177], v141 offset:3072
	s_add_u32 s10, s6, s8
	s_addc_u32 s11, s7, s9
	s_add_u32 s10, s10, 0x2300100
	s_addc_u32 s11, s11, 0
	s_add_u32 s23, s69, s8
	s_addc_u32 s33, s70, s9
	s_cmpk_eq_i32 s8, 0x700
	s_cselect_b32 s13, s3, s11
	s_cselect_b32 s12, s2, s10
	s_cselect_b32 s11, s1, s33
	s_cselect_b32 s10, s0, s23
	s_mov_b32 m0, s72
	v_lshl_add_u64 v[210:211], v[134:135], 0, s[8:9]
	ds_read_b128 v[178:181], v142
	ds_read_b128 v[182:185], v142 offset:1024
	ds_read_b128 v[186:189], v142 offset:2048
	ds_read_b128 v[190:193], v142 offset:3072
	ds_read_b128 v[194:197], v142 offset:4096
	ds_read_b128 v[198:201], v142 offset:5120
	ds_read_b128 v[202:205], v142 offset:6144
	ds_read_b128 v[206:209], v142 offset:7168
	global_load_lds_dwordx4 v[210:211], off
	v_lshl_add_u64 v[210:211], v[136:137], 0, s[8:9]
	s_mov_b32 m0, s73
	s_nop 0
	global_load_lds_dwordx4 v[210:211], off
	s_waitcnt vmcnt(8)
	s_waitcnt lgkmcnt(0)
	s_barrier
	s_setprio 1
	v_mfma_f32_16x16x32_bf16 v[124:127], v[146:149], v[178:181], v[124:127]
	v_mfma_f32_16x16x32_bf16 v[120:123], v[154:157], v[178:181], v[120:123]
	v_mfma_f32_16x16x32_bf16 v[108:111], v[146:149], v[186:189], v[108:111]
	v_mfma_f32_16x16x32_bf16 v[104:107], v[154:157], v[186:189], v[104:107]
	v_mfma_f32_16x16x32_bf16 v[92:95], v[146:149], v[194:197], v[92:95]
	v_mfma_f32_16x16x32_bf16 v[88:91], v[154:157], v[194:197], v[88:91]
	v_mfma_f32_16x16x32_bf16 v[76:79], v[146:149], v[202:205], v[76:79]
	v_mfma_f32_16x16x32_bf16 v[72:75], v[154:157], v[202:205], v[72:75]
	v_mfma_f32_16x16x32_bf16 v[124:127], v[150:153], v[182:185], v[124:127]
	v_mfma_f32_16x16x32_bf16 v[120:123], v[158:161], v[182:185], v[120:123]
	v_mfma_f32_16x16x32_bf16 v[108:111], v[150:153], v[190:193], v[108:111]
	v_mfma_f32_16x16x32_bf16 v[104:107], v[158:161], v[190:193], v[104:107]
	v_mfma_f32_16x16x32_bf16 v[92:95], v[150:153], v[198:201], v[92:95]
	v_mfma_f32_16x16x32_bf16 v[88:91], v[158:161], v[198:201], v[88:91]
	v_mfma_f32_16x16x32_bf16 v[76:79], v[150:153], v[206:209], v[76:79]
	v_mfma_f32_16x16x32_bf16 v[72:75], v[158:161], v[206:209], v[72:75]
	v_mfma_f32_16x16x32_bf16 v[116:119], v[162:165], v[178:181], v[116:119]
	v_mfma_f32_16x16x32_bf16 v[112:115], v[170:173], v[178:181], v[112:115]
	v_mfma_f32_16x16x32_bf16 v[100:103], v[162:165], v[186:189], v[100:103]
	v_mfma_f32_16x16x32_bf16 v[96:99], v[170:173], v[186:189], v[96:99]
	v_mfma_f32_16x16x32_bf16 v[84:87], v[162:165], v[194:197], v[84:87]
	v_mfma_f32_16x16x32_bf16 v[80:83], v[170:173], v[194:197], v[80:83]
	v_mfma_f32_16x16x32_bf16 v[68:71], v[162:165], v[202:205], v[68:71]
	v_mfma_f32_16x16x32_bf16 v[64:67], v[170:173], v[202:205], v[64:67]
	v_mfma_f32_16x16x32_bf16 v[116:119], v[166:169], v[182:185], v[116:119]
	v_mfma_f32_16x16x32_bf16 v[112:115], v[174:177], v[182:185], v[112:115]
	v_mfma_f32_16x16x32_bf16 v[100:103], v[166:169], v[190:193], v[100:103]
	v_mfma_f32_16x16x32_bf16 v[96:99], v[174:177], v[190:193], v[96:99]
	v_mfma_f32_16x16x32_bf16 v[84:87], v[166:169], v[198:201], v[84:87]
	v_mfma_f32_16x16x32_bf16 v[80:83], v[174:177], v[198:201], v[80:83]
	v_mfma_f32_16x16x32_bf16 v[68:71], v[166:169], v[206:209], v[68:71]
	v_mfma_f32_16x16x32_bf16 v[64:67], v[174:177], v[206:209], v[64:67]
	s_setprio 0
	s_barrier
	s_mov_b32 m0, s74
	v_lshl_add_u64 v[210:211], s[10:11], 0, v[132:133]
	s_add_u32 s82, s10, 0x40000
	ds_read_b128 v[178:181], v142 offset:16384
	ds_read_b128 v[182:185], v142 offset:17408
	ds_read_b128 v[186:189], v142 offset:18432
	ds_read_b128 v[190:193], v142 offset:19456
	ds_read_b128 v[194:197], v142 offset:20480
	ds_read_b128 v[198:201], v142 offset:21504
	ds_read_b128 v[202:205], v142 offset:22528
	ds_read_b128 v[206:209], v142 offset:23552
	global_load_lds_dwordx4 v[210:211], off
	v_lshl_add_u64 v[212:213], s[10:11], 0, v[130:131]
	s_mov_b32 m0, s75
	s_addc_u32 s83, s11, 0
	global_load_lds_dwordx4 v[212:213], off
	v_lshl_add_u64 v[214:215], s[82:83], 0, v[132:133]
	s_mov_b32 m0, s76
	v_lshl_add_u64 v[216:217], s[12:13], 0, v[130:131]
	global_load_lds_dwordx4 v[214:215], off
	v_lshl_add_u64 v[214:215], s[82:83], 0, v[130:131]
	s_mov_b32 m0, s77
	s_nop 0
	global_load_lds_dwordx4 v[214:215], off
	v_lshl_add_u64 v[214:215], s[12:13], 0, v[132:133]
	s_mov_b32 m0, s17
	s_nop 0
	global_load_lds_dwordx4 v[214:215], off
	s_mov_b32 m0, s20
	s_nop 0
	global_load_lds_dwordx4 v[216:217], off
	s_waitcnt vmcnt(8)
	s_waitcnt lgkmcnt(0)
	s_barrier
	s_setprio 1
	v_mfma_f32_16x16x32_bf16 v[60:63], v[146:149], v[178:181], v[60:63]
	v_mfma_f32_16x16x32_bf16 v[56:59], v[154:157], v[178:181], v[56:59]
	v_mfma_f32_16x16x32_bf16 v[44:47], v[146:149], v[186:189], v[44:47]
	v_mfma_f32_16x16x32_bf16 v[40:43], v[154:157], v[186:189], v[40:43]
	v_mfma_f32_16x16x32_bf16 v[28:31], v[146:149], v[194:197], v[28:31]
	v_mfma_f32_16x16x32_bf16 v[24:27], v[154:157], v[194:197], v[24:27]
	v_mfma_f32_16x16x32_bf16 v[12:15], v[146:149], v[202:205], v[12:15]
	v_mfma_f32_16x16x32_bf16 v[8:11], v[154:157], v[202:205], v[8:11]
	v_mfma_f32_16x16x32_bf16 v[60:63], v[150:153], v[182:185], v[60:63]
	v_mfma_f32_16x16x32_bf16 v[56:59], v[158:161], v[182:185], v[56:59]
	v_mfma_f32_16x16x32_bf16 v[44:47], v[150:153], v[190:193], v[44:47]
	v_mfma_f32_16x16x32_bf16 v[40:43], v[158:161], v[190:193], v[40:43]
	v_mfma_f32_16x16x32_bf16 v[28:31], v[150:153], v[198:201], v[28:31]
	v_mfma_f32_16x16x32_bf16 v[24:27], v[158:161], v[198:201], v[24:27]
	v_mfma_f32_16x16x32_bf16 v[12:15], v[150:153], v[206:209], v[12:15]
	v_mfma_f32_16x16x32_bf16 v[8:11], v[158:161], v[206:209], v[8:11]
	v_mfma_f32_16x16x32_bf16 v[52:55], v[162:165], v[178:181], v[52:55]
	v_mfma_f32_16x16x32_bf16 v[48:51], v[170:173], v[178:181], v[48:51]
	v_mfma_f32_16x16x32_bf16 v[36:39], v[162:165], v[186:189], v[36:39]
	v_mfma_f32_16x16x32_bf16 v[32:35], v[170:173], v[186:189], v[32:35]
	v_mfma_f32_16x16x32_bf16 v[20:23], v[162:165], v[194:197], v[20:23]
	v_mfma_f32_16x16x32_bf16 v[16:19], v[170:173], v[194:197], v[16:19]
	v_mfma_f32_16x16x32_bf16 v[4:7], v[162:165], v[202:205], v[4:7]
	v_mfma_f32_16x16x32_bf16 v[0:3], v[170:173], v[202:205], v[0:3]
	v_mfma_f32_16x16x32_bf16 v[52:55], v[166:169], v[182:185], v[52:55]
	v_mfma_f32_16x16x32_bf16 v[48:51], v[174:177], v[182:185], v[48:51]
	v_mfma_f32_16x16x32_bf16 v[36:39], v[166:169], v[190:193], v[36:39]
	v_mfma_f32_16x16x32_bf16 v[32:35], v[174:177], v[190:193], v[32:35]
	v_mfma_f32_16x16x32_bf16 v[20:23], v[166:169], v[198:201], v[20:23]
	v_mfma_f32_16x16x32_bf16 v[16:19], v[174:177], v[198:201], v[16:19]
	v_mfma_f32_16x16x32_bf16 v[4:7], v[166:169], v[206:209], v[4:7]
	v_mfma_f32_16x16x32_bf16 v[0:3], v[174:177], v[206:209], v[0:3]
	s_setprio 0
	s_barrier
	ds_read_b128 v[146:149], v143
	ds_read_b128 v[150:153], v143 offset:1024
	ds_read_b128 v[154:157], v143 offset:2048
	ds_read_b128 v[158:161], v143 offset:3072
	ds_read_b128 v[162:165], v144
	ds_read_b128 v[166:169], v144 offset:1024
	ds_read_b128 v[170:173], v144 offset:2048
	ds_read_b128 v[174:177], v144 offset:3072
	s_add_u32 s12, s12, 0x40000
	s_addc_u32 s13, s13, 0
	s_mov_b32 m0, s21
	v_lshl_add_u64 v[218:219], s[12:13], 0, v[132:133]
	ds_read_b128 v[178:181], v142 offset:32768
	ds_read_b128 v[182:185], v142 offset:33792
	ds_read_b128 v[186:189], v142 offset:34816
	ds_read_b128 v[190:193], v142 offset:35840
	ds_read_b128 v[194:197], v142 offset:36864
	ds_read_b128 v[198:201], v142 offset:37888
	ds_read_b128 v[202:205], v142 offset:38912
	ds_read_b128 v[206:209], v142 offset:39936
	global_load_lds_dwordx4 v[218:219], off
	v_lshl_add_u64 v[218:219], s[12:13], 0, v[130:131]
	s_mov_b32 m0, s58
	s_nop 0
	global_load_lds_dwordx4 v[218:219], off
	s_waitcnt vmcnt(8)
	s_waitcnt lgkmcnt(0)
	s_barrier
	s_setprio 1
	v_mfma_f32_16x16x32_bf16 v[124:127], v[146:149], v[178:181], v[124:127]
	v_mfma_f32_16x16x32_bf16 v[120:123], v[154:157], v[178:181], v[120:123]
	v_mfma_f32_16x16x32_bf16 v[108:111], v[146:149], v[186:189], v[108:111]
	v_mfma_f32_16x16x32_bf16 v[104:107], v[154:157], v[186:189], v[104:107]
	v_mfma_f32_16x16x32_bf16 v[92:95], v[146:149], v[194:197], v[92:95]
	v_mfma_f32_16x16x32_bf16 v[88:91], v[154:157], v[194:197], v[88:91]
	v_mfma_f32_16x16x32_bf16 v[76:79], v[146:149], v[202:205], v[76:79]
	v_mfma_f32_16x16x32_bf16 v[72:75], v[154:157], v[202:205], v[72:75]
	v_mfma_f32_16x16x32_bf16 v[124:127], v[150:153], v[182:185], v[124:127]
	v_mfma_f32_16x16x32_bf16 v[120:123], v[158:161], v[182:185], v[120:123]
	v_mfma_f32_16x16x32_bf16 v[108:111], v[150:153], v[190:193], v[108:111]
	v_mfma_f32_16x16x32_bf16 v[104:107], v[158:161], v[190:193], v[104:107]
	v_mfma_f32_16x16x32_bf16 v[92:95], v[150:153], v[198:201], v[92:95]
	v_mfma_f32_16x16x32_bf16 v[88:91], v[158:161], v[198:201], v[88:91]
	v_mfma_f32_16x16x32_bf16 v[76:79], v[150:153], v[206:209], v[76:79]
	v_mfma_f32_16x16x32_bf16 v[72:75], v[158:161], v[206:209], v[72:75]
	v_mfma_f32_16x16x32_bf16 v[116:119], v[162:165], v[178:181], v[116:119]
	v_mfma_f32_16x16x32_bf16 v[112:115], v[170:173], v[178:181], v[112:115]
	v_mfma_f32_16x16x32_bf16 v[100:103], v[162:165], v[186:189], v[100:103]
	v_mfma_f32_16x16x32_bf16 v[96:99], v[170:173], v[186:189], v[96:99]
	v_mfma_f32_16x16x32_bf16 v[84:87], v[162:165], v[194:197], v[84:87]
	v_mfma_f32_16x16x32_bf16 v[80:83], v[170:173], v[194:197], v[80:83]
	v_mfma_f32_16x16x32_bf16 v[68:71], v[162:165], v[202:205], v[68:71]
	v_mfma_f32_16x16x32_bf16 v[64:67], v[170:173], v[202:205], v[64:67]
	v_mfma_f32_16x16x32_bf16 v[116:119], v[166:169], v[182:185], v[116:119]
	v_mfma_f32_16x16x32_bf16 v[112:115], v[174:177], v[182:185], v[112:115]
	v_mfma_f32_16x16x32_bf16 v[100:103], v[166:169], v[190:193], v[100:103]
	v_mfma_f32_16x16x32_bf16 v[96:99], v[174:177], v[190:193], v[96:99]
	v_mfma_f32_16x16x32_bf16 v[84:87], v[166:169], v[198:201], v[84:87]
	v_mfma_f32_16x16x32_bf16 v[80:83], v[174:177], v[198:201], v[80:83]
	v_mfma_f32_16x16x32_bf16 v[68:71], v[166:169], v[206:209], v[68:71]
	v_mfma_f32_16x16x32_bf16 v[64:67], v[174:177], v[206:209], v[64:67]
	s_setprio 0
	s_barrier
	s_mov_b32 m0, s78
	v_lshl_add_u64 v[210:211], v[210:211], 0, s[4:5]
	s_add_u32 s10, s10, 0x40080
	ds_read_b128 v[178:181], v142 offset:49152
	ds_read_b128 v[182:185], v142 offset:50176
	ds_read_b128 v[186:189], v142 offset:51200
	ds_read_b128 v[190:193], v142 offset:52224
	ds_read_b128 v[194:197], v142 offset:53248
	ds_read_b128 v[198:201], v142 offset:54272
	ds_read_b128 v[202:205], v142 offset:55296
	ds_read_b128 v[206:209], v142 offset:56320
	global_load_lds_dwordx4 v[210:211], off
	v_lshl_add_u64 v[210:211], v[212:213], 0, s[4:5]
	s_mov_b32 m0, s79
	s_addc_u32 s11, s11, 0
	global_load_lds_dwordx4 v[210:211], off
	v_lshl_add_u64 v[210:211], s[10:11], 0, v[132:133]
	s_mov_b32 m0, s80
	s_nop 0
	global_load_lds_dwordx4 v[210:211], off
	v_lshl_add_u64 v[210:211], s[10:11], 0, v[130:131]
	s_mov_b32 m0, s81
	s_nop 0
	global_load_lds_dwordx4 v[210:211], off
	v_lshl_add_u64 v[210:211], v[214:215], 0, s[4:5]
	s_mov_b32 m0, s65
	s_nop 0
	global_load_lds_dwordx4 v[210:211], off
	v_lshl_add_u64 v[210:211], v[216:217], 0, s[4:5]
	s_mov_b32 m0, s68
	s_nop 0
	global_load_lds_dwordx4 v[210:211], off
	s_waitcnt vmcnt(8)
	s_waitcnt lgkmcnt(0)
	s_barrier
	s_setprio 1
	v_mfma_f32_16x16x32_bf16 v[60:63], v[146:149], v[178:181], v[60:63]
	v_mfma_f32_16x16x32_bf16 v[56:59], v[154:157], v[178:181], v[56:59]
	v_mfma_f32_16x16x32_bf16 v[44:47], v[146:149], v[186:189], v[44:47]
	v_mfma_f32_16x16x32_bf16 v[40:43], v[154:157], v[186:189], v[40:43]
	v_mfma_f32_16x16x32_bf16 v[28:31], v[146:149], v[194:197], v[28:31]
	v_mfma_f32_16x16x32_bf16 v[24:27], v[154:157], v[194:197], v[24:27]
	v_mfma_f32_16x16x32_bf16 v[12:15], v[146:149], v[202:205], v[12:15]
	v_mfma_f32_16x16x32_bf16 v[8:11], v[154:157], v[202:205], v[8:11]
	v_mfma_f32_16x16x32_bf16 v[60:63], v[150:153], v[182:185], v[60:63]
	v_mfma_f32_16x16x32_bf16 v[56:59], v[158:161], v[182:185], v[56:59]
	v_mfma_f32_16x16x32_bf16 v[44:47], v[150:153], v[190:193], v[44:47]
	v_mfma_f32_16x16x32_bf16 v[40:43], v[158:161], v[190:193], v[40:43]
	v_mfma_f32_16x16x32_bf16 v[28:31], v[150:153], v[198:201], v[28:31]
	v_mfma_f32_16x16x32_bf16 v[24:27], v[158:161], v[198:201], v[24:27]
	v_mfma_f32_16x16x32_bf16 v[12:15], v[150:153], v[206:209], v[12:15]
	v_mfma_f32_16x16x32_bf16 v[8:11], v[158:161], v[206:209], v[8:11]
	v_mfma_f32_16x16x32_bf16 v[52:55], v[162:165], v[178:181], v[52:55]
	v_mfma_f32_16x16x32_bf16 v[48:51], v[170:173], v[178:181], v[48:51]
	v_mfma_f32_16x16x32_bf16 v[36:39], v[162:165], v[186:189], v[36:39]
	v_mfma_f32_16x16x32_bf16 v[32:35], v[170:173], v[186:189], v[32:35]
	v_mfma_f32_16x16x32_bf16 v[20:23], v[162:165], v[194:197], v[20:23]
	v_mfma_f32_16x16x32_bf16 v[16:19], v[170:173], v[194:197], v[16:19]
	v_mfma_f32_16x16x32_bf16 v[4:7], v[162:165], v[202:205], v[4:7]
	v_mfma_f32_16x16x32_bf16 v[0:3], v[170:173], v[202:205], v[0:3]
	v_mfma_f32_16x16x32_bf16 v[52:55], v[166:169], v[182:185], v[52:55]
	v_mfma_f32_16x16x32_bf16 v[48:51], v[174:177], v[182:185], v[48:51]
	v_mfma_f32_16x16x32_bf16 v[36:39], v[166:169], v[190:193], v[36:39]
	v_mfma_f32_16x16x32_bf16 v[32:35], v[174:177], v[190:193], v[32:35]
	v_mfma_f32_16x16x32_bf16 v[20:23], v[166:169], v[198:201], v[20:23]
	v_mfma_f32_16x16x32_bf16 v[16:19], v[174:177], v[198:201], v[16:19]
	v_mfma_f32_16x16x32_bf16 v[4:7], v[166:169], v[206:209], v[4:7]
	v_mfma_f32_16x16x32_bf16 v[0:3], v[174:177], v[206:209], v[0:3]
	s_setprio 0
	s_barrier
	s_add_i32 s71, s71, 2
	s_add_u32 s8, s8, 0x100
	s_addc_u32 s9, s9, 0
	s_cmp_gt_u32 s71, 13
	s_cbranch_scc0 .LBB0_437
	s_add_u32 s4, s28, 0x2f41000
	s_addc_u32 s5, s29, 0
	s_lshl_b32 s0, s16, 8
	s_add_i32 s64, s64, s0
	v_or_b32_e32 v130, s64, v140
	v_mov_b32_e32 v131, 0
	v_lshl_add_u64 v[132:133], v[130:131], 2, s[4:5]
	global_load_dword v149, v[132:133], off
	v_lshl_or_b32 v134, v138, 2, s59
	v_mov_b32_e32 v148, 0x358637bd
	s_lshl_b32 s13, s15, 8
	s_mov_b32 s6, 0x800000
	s_movk_i32 s0, 0x36c
	v_or_b32_e32 v146, s13, v134
	s_and_b32 s9, s13, 0x300
	v_mov_b32_e32 v150, s13
	s_lshl_b32 s13, s64, 2
	v_mov_b32_e32 v142, 0x80
	s_movk_i32 s10, 0xec
	v_lshlrev_b32_e32 v138, 1, v134
	v_bitop3_b32 v134, v134, s0, v150 bitop3:0xc8
	s_and_b32 s0, s13, 0xfffffc00
	v_bitop3_b32 v154, v146, s10, v142 bitop3:0xc8
	s_or_b32 s10, s0, s9
	s_mov_b32 s1, 0x4880000
	s_cmp_gt_u32 s15, 3
	v_mov_b32_e32 v136, 0xcf
	s_mov_b32 s2, 0x2b00000
	s_cselect_b32 s0, s1, 0x4080000
	s_movk_i32 s3, 0x37c
	s_movk_i32 s8, 0x3ec
	v_bitop3_b32 v152, s64, v136, v140 bitop3:0xc8
	s_cselect_b32 s1, s2, 0x2700000
	s_add_u32 s2, s26, s0
	v_bitop3_b32 v136, v146, s3, 16 bitop3:0xc8
	v_bitop3_b32 v153, v146, s8, v142 bitop3:0xc8
	v_or_b32_e32 v152, s10, v152
	s_addc_u32 s3, s27, 0
	s_movk_i32 s7, 0x7c
	s_movk_i32 s11, 0x3fc
	v_mov_b32_e32 v144, 0x90
	s_movk_i32 s12, 0xfc
	v_lshlrev_b64 v[150:151], 12, v[130:131]
	v_lshlrev_b32_e32 v142, 2, v153
	v_ashrrev_i32_e32 v153, 31, v152
	s_add_u32 s0, s28, s1
	v_mov_b32_e32 v147, v131
	v_bitop3_b32 v140, v146, s7, 16 bitop3:0xc8
	v_bitop3_b32 v155, v146, s11, v144 bitop3:0xc8
	v_bitop3_b32 v167, v146, s12, v144 bitop3:0xc8
	v_lshlrev_b32_e32 v146, 2, v134
	v_lshlrev_b64 v[152:153], 9, v[152:153]
	v_lshl_add_u64 v[150:151], s[2:3], 0, v[150:151]
	s_addc_u32 s1, s29, 0
	v_mov_b32_e32 v139, v131
	v_lshlrev_b32_e32 v144, 2, v136
	v_lshlrev_b32_e32 v134, 1, v140
	v_lshlrev_b32_e32 v136, 1, v154
	v_lshlrev_b32_e32 v140, 2, v155
	v_lshl_add_u64 v[154:155], v[150:151], 0, v[146:147]
	v_lshl_add_u64 v[152:153], s[0:1], 0, v[152:153]
	v_mov_b32_e32 v145, v131
	v_mov_b32_e32 v135, v131
	v_mov_b32_e32 v143, v131
	v_mov_b32_e32 v137, v131
	v_lshl_add_u64 v[156:157], v[150:151], 0, v[144:145]
	v_lshl_add_u64 v[162:163], v[152:153], 0, v[134:135]
	v_mov_b32_e32 v141, v131
	v_lshl_add_u64 v[158:159], v[150:151], 0, v[142:143]
	v_lshl_add_u64 v[164:165], v[152:153], 0, v[136:137]
	v_lshl_add_u64 v[150:151], v[150:151], 0, v[140:141]
	s_movk_i32 s7, 0xdf
	s_movk_i32 s8, 0xef
	s_cmpk_lt_u32 s14, 0x100
	s_waitcnt vmcnt(0)
	v_fmamk_f32 v149, v149, 0x3a800000, v148
	v_mul_f32_e32 v160, 0x4b800000, v149
	v_cmp_gt_f32_e32 vcc, s6, v149
	s_nop 1
	v_cndmask_b32_e32 v149, v149, v160, vcc
	v_rsq_f32_e32 v149, v149
	v_lshl_add_u64 v[160:161], v[152:153], 0, v[138:139]
	v_mul_f32_e32 v166, 0x45800000, v149
	v_cndmask_b32_e32 v166, v149, v166, vcc
	v_pk_mul_f32 v[126:127], v[126:127], v[166:167] op_sel_hi:[1,0]
	v_pk_mul_f32 v[124:125], v[124:125], v[166:167] op_sel_hi:[1,0]
	v_pk_mul_f32 v[120:121], v[120:121], v[166:167] op_sel_hi:[1,0]
	global_store_dwordx4 v[154:155], v[124:127], off
	v_pk_mul_f32 v[122:123], v[122:123], v[166:167] op_sel_hi:[1,0]
	v_pk_mul_f32 v[116:117], v[116:117], v[166:167] op_sel_hi:[1,0]
	v_cvt_pk_bf16_f32 v124, v124, v125
	v_cvt_pk_bf16_f32 v125, v126, v127
	global_store_dwordx2 v[160:161], v[124:125], off
	global_store_dwordx4 v[156:157], v[120:123], off
	v_pk_mul_f32 v[118:119], v[118:119], v[166:167] op_sel_hi:[1,0]
	v_pk_mul_f32 v[112:113], v[112:113], v[166:167] op_sel_hi:[1,0]
	v_cvt_pk_bf16_f32 v120, v120, v121
	v_cvt_pk_bf16_f32 v121, v122, v123
	global_store_dwordx2 v[162:163], v[120:121], off
	global_store_dwordx4 v[158:159], v[116:119], off
	v_pk_mul_f32 v[114:115], v[114:115], v[166:167] op_sel_hi:[1,0]
	v_bitop3_b32 v120, v130, s7, 16 bitop3:0xc8
	v_cvt_pk_bf16_f32 v116, v116, v117
	v_cvt_pk_bf16_f32 v117, v118, v119
	global_store_dwordx2 v[164:165], v[116:117], off
	global_store_dwordx4 v[150:151], v[112:115], off
	v_cvt_pk_bf16_f32 v116, v112, v113
	v_cvt_pk_bf16_f32 v117, v114, v115
	v_or_b32_e32 v120, s10, v120
	v_ashrrev_i32_e32 v121, 31, v120
	v_lshlrev_b32_e32 v112, 1, v167
	v_mov_b32_e32 v113, v131
	v_lshl_add_u64 v[114:115], v[152:153], 0, v[112:113]
	global_store_dwordx2 v[114:115], v[116:117], off
	v_or_b32_e32 v114, 16, v130
	v_mov_b32_e32 v115, v131
	v_lshl_add_u64 v[116:117], v[114:115], 2, s[4:5]
	global_load_dword v149, v[116:117], off
	v_lshlrev_b64 v[114:115], 12, v[114:115]
	v_lshlrev_b64 v[120:121], 9, v[120:121]
	v_lshl_add_u64 v[114:115], s[2:3], 0, v[114:115]
	v_lshl_add_u64 v[122:123], v[114:115], 0, v[146:147]
	v_lshl_add_u64 v[120:121], s[0:1], 0, v[120:121]
	v_lshl_add_u64 v[150:151], v[120:121], 0, v[138:139]
	v_lshl_add_u64 v[124:125], v[114:115], 0, v[144:145]
	v_mov_b32_e32 v117, v131
	v_or_b32_e32 v116, 32, v130
	v_lshl_add_u64 v[126:127], v[114:115], 0, v[142:143]
	v_lshl_add_u64 v[154:155], v[120:121], 0, v[136:137]
	v_lshl_add_u64 v[118:119], v[116:117], 2, s[4:5]
	v_lshl_add_u64 v[114:115], v[114:115], 0, v[140:141]
	s_waitcnt vmcnt(0)
	v_fmamk_f32 v149, v149, 0x3a800000, v148
	v_mul_f32_e32 v152, 0x4b800000, v149
	v_cmp_gt_f32_e32 vcc, s6, v149
	s_nop 1
	v_cndmask_b32_e32 v149, v149, v152, vcc
	v_rsq_f32_e32 v149, v149
	v_lshl_add_u64 v[152:153], v[120:121], 0, v[134:135]
	v_lshl_add_u64 v[120:121], v[120:121], 0, v[112:113]
	v_mul_f32_e32 v156, 0x45800000, v149
	v_cndmask_b32_e32 v156, v149, v156, vcc
	v_pk_mul_f32 v[110:111], v[110:111], v[156:157] op_sel_hi:[1,0]
	v_pk_mul_f32 v[108:109], v[108:109], v[156:157] op_sel_hi:[1,0]
	v_pk_mul_f32 v[104:105], v[104:105], v[156:157] op_sel_hi:[1,0]
	global_store_dwordx4 v[122:123], v[108:111], off
	v_pk_mul_f32 v[106:107], v[106:107], v[156:157] op_sel_hi:[1,0]
	v_pk_mul_f32 v[100:101], v[100:101], v[156:157] op_sel_hi:[1,0]
	v_cvt_pk_bf16_f32 v108, v108, v109
	v_cvt_pk_bf16_f32 v109, v110, v111
	global_store_dwordx2 v[150:151], v[108:109], off
	global_store_dwordx4 v[124:125], v[104:107], off
	v_pk_mul_f32 v[102:103], v[102:103], v[156:157] op_sel_hi:[1,0]
	v_pk_mul_f32 v[96:97], v[96:97], v[156:157] op_sel_hi:[1,0]
	v_cvt_pk_bf16_f32 v104, v104, v105
	v_cvt_pk_bf16_f32 v105, v106, v107
	global_store_dwordx2 v[152:153], v[104:105], off
	global_store_dwordx4 v[126:127], v[100:103], off
	v_pk_mul_f32 v[98:99], v[98:99], v[156:157] op_sel_hi:[1,0]
	s_nop 0
	v_cvt_pk_bf16_f32 v100, v100, v101
	v_cvt_pk_bf16_f32 v101, v102, v103
	global_store_dwordx2 v[154:155], v[100:101], off
	global_store_dwordx4 v[114:115], v[96:99], off
	v_bitop3_b32 v102, v130, s8, 32 bitop3:0xc8
	v_or_b32_e32 v102, s10, v102
	v_cvt_pk_bf16_f32 v96, v96, v97
	v_cvt_pk_bf16_f32 v97, v98, v99
	global_store_dwordx2 v[120:121], v[96:97], off
	global_load_dword v114, v[118:119], off
	v_lshlrev_b64 v[98:99], 12, v[116:117]
	v_ashrrev_i32_e32 v103, 31, v102
	v_lshlrev_b64 v[102:103], 9, v[102:103]
	v_lshl_add_u64 v[98:99], s[2:3], 0, v[98:99]
	v_lshl_add_u64 v[104:105], v[98:99], 0, v[146:147]
	v_lshl_add_u64 v[102:103], s[0:1], 0, v[102:103]
	v_lshl_add_u64 v[110:111], v[102:103], 0, v[138:139]
	v_lshl_add_u64 v[106:107], v[98:99], 0, v[144:145]
	v_mov_b32_e32 v97, v131
	v_or_b32_e32 v96, 48, v130
	v_lshl_add_u64 v[108:109], v[98:99], 0, v[142:143]
	v_lshl_add_u64 v[116:117], v[102:103], 0, v[136:137]
	v_lshl_add_u64 v[100:101], v[96:97], 2, s[4:5]
	v_lshl_add_u64 v[98:99], v[98:99], 0, v[140:141]
	s_movk_i32 s4, 0xff
	s_movk_i32 s5, 0xcf
	s_waitcnt vmcnt(0)
	v_fmamk_f32 v114, v114, 0x3a800000, v148
	v_mul_f32_e32 v115, 0x4b800000, v114
	v_cmp_gt_f32_e32 vcc, s6, v114
	s_nop 1
	v_cndmask_b32_e32 v114, v114, v115, vcc
	v_rsq_f32_e32 v118, v114
	v_lshl_add_u64 v[114:115], v[102:103], 0, v[134:135]
	v_lshl_add_u64 v[102:103], v[102:103], 0, v[112:113]
	v_mul_f32_e32 v119, 0x45800000, v118
	v_cndmask_b32_e32 v118, v118, v119, vcc
	v_pk_mul_f32 v[94:95], v[94:95], v[118:119] op_sel_hi:[1,0]
	v_pk_mul_f32 v[92:93], v[92:93], v[118:119] op_sel_hi:[1,0]
	v_pk_mul_f32 v[88:89], v[88:89], v[118:119] op_sel_hi:[1,0]
	global_store_dwordx4 v[104:105], v[92:95], off
	v_pk_mul_f32 v[90:91], v[90:91], v[118:119] op_sel_hi:[1,0]
	v_pk_mul_f32 v[84:85], v[84:85], v[118:119] op_sel_hi:[1,0]
	v_cvt_pk_bf16_f32 v92, v92, v93
	v_cvt_pk_bf16_f32 v93, v94, v95
	global_store_dwordx2 v[110:111], v[92:93], off
	global_store_dwordx4 v[106:107], v[88:91], off
	v_pk_mul_f32 v[86:87], v[86:87], v[118:119] op_sel_hi:[1,0]
	v_pk_mul_f32 v[80:81], v[80:81], v[118:119] op_sel_hi:[1,0]
	v_cvt_pk_bf16_f32 v88, v88, v89
	v_cvt_pk_bf16_f32 v89, v90, v91
	global_store_dwordx2 v[114:115], v[88:89], off
	global_store_dwordx4 v[108:109], v[84:87], off
	v_pk_mul_f32 v[82:83], v[82:83], v[118:119] op_sel_hi:[1,0]
	s_nop 0
	v_cvt_pk_bf16_f32 v84, v84, v85
	v_cvt_pk_bf16_f32 v85, v86, v87
	global_store_dwordx2 v[116:117], v[84:85], off
	global_store_dwordx4 v[98:99], v[80:83], off
	s_nop 1
	v_cvt_pk_bf16_f32 v80, v80, v81
	v_cvt_pk_bf16_f32 v81, v82, v83
	global_store_dwordx2 v[102:103], v[80:81], off
	global_load_dword v92, v[100:101], off
	v_lshlrev_b64 v[80:81], 12, v[96:97]
	v_bitop3_b32 v82, v130, s4, 48 bitop3:0xc8
	v_or_b32_e32 v82, s10, v82
	v_ashrrev_i32_e32 v83, 31, v82
	v_lshlrev_b64 v[82:83], 9, v[82:83]
	v_lshl_add_u64 v[80:81], s[2:3], 0, v[80:81]
	v_lshl_add_u64 v[84:85], v[80:81], 0, v[146:147]
	v_lshl_add_u64 v[82:83], s[0:1], 0, v[82:83]
	v_lshl_add_u64 v[90:91], v[82:83], 0, v[138:139]
	v_lshl_add_u64 v[86:87], v[80:81], 0, v[144:145]
	v_lshl_add_u64 v[88:89], v[80:81], 0, v[142:143]
	v_lshl_add_u64 v[94:95], v[82:83], 0, v[136:137]
	v_lshl_add_u64 v[80:81], v[80:81], 0, v[140:141]
	s_waitcnt vmcnt(0)
	v_fmamk_f32 v92, v92, 0x3a800000, v148
	v_mul_f32_e32 v93, 0x4b800000, v92
	v_cmp_gt_f32_e32 vcc, s6, v92
	s_nop 1
	v_cndmask_b32_e32 v92, v92, v93, vcc
	v_rsq_f32_e32 v96, v92
	v_lshl_add_u64 v[92:93], v[82:83], 0, v[134:135]
	v_lshl_add_u64 v[82:83], v[82:83], 0, v[112:113]
	v_mul_f32_e32 v97, 0x45800000, v96
	v_cndmask_b32_e32 v96, v96, v97, vcc
	v_pk_mul_f32 v[78:79], v[78:79], v[96:97] op_sel_hi:[1,0]
	v_pk_mul_f32 v[76:77], v[76:77], v[96:97] op_sel_hi:[1,0]
	v_pk_mul_f32 v[72:73], v[72:73], v[96:97] op_sel_hi:[1,0]
	global_store_dwordx4 v[84:85], v[76:79], off
	v_pk_mul_f32 v[74:75], v[74:75], v[96:97] op_sel_hi:[1,0]
	v_pk_mul_f32 v[68:69], v[68:69], v[96:97] op_sel_hi:[1,0]
	v_cvt_pk_bf16_f32 v76, v76, v77
	v_cvt_pk_bf16_f32 v77, v78, v79
	global_store_dwordx2 v[90:91], v[76:77], off
	global_store_dwordx4 v[86:87], v[72:75], off
	v_pk_mul_f32 v[70:71], v[70:71], v[96:97] op_sel_hi:[1,0]
	v_pk_mul_f32 v[64:65], v[64:65], v[96:97] op_sel_hi:[1,0]
	v_cvt_pk_bf16_f32 v72, v72, v73
	v_cvt_pk_bf16_f32 v73, v74, v75
	global_store_dwordx2 v[92:93], v[72:73], off
	global_store_dwordx4 v[88:89], v[68:71], off
	v_pk_mul_f32 v[66:67], v[66:67], v[96:97] op_sel_hi:[1,0]
	s_nop 0
	v_cvt_pk_bf16_f32 v68, v68, v69
	v_cvt_pk_bf16_f32 v69, v70, v71
	global_store_dwordx2 v[94:95], v[68:69], off
	global_store_dwordx4 v[80:81], v[64:67], off
	s_nop 1
	v_cvt_pk_bf16_f32 v64, v64, v65
	v_cvt_pk_bf16_f32 v65, v66, v67
	global_store_dwordx2 v[82:83], v[64:65], off
	global_load_dword v76, v[132:133], off offset:512
	v_add_u32_e32 v64, 0x80, v130
	v_mov_b32_e32 v65, v131
	v_lshlrev_b32_e32 v68, 2, v64
	v_lshlrev_b64 v[66:67], 12, v[64:65]
	v_and_b32_e32 v65, 0xfffffc00, v68
	v_or_b32_e32 v81, s9, v65
	v_and_or_b32 v64, v64, s5, v81
	v_ashrrev_i32_e32 v65, 31, v64
	v_lshlrev_b64 v[64:65], 9, v[64:65]
	v_lshl_add_u64 v[66:67], s[2:3], 0, v[66:67]
	v_lshl_add_u64 v[68:69], v[66:67], 0, v[146:147]
	v_lshl_add_u64 v[64:65], s[0:1], 0, v[64:65]
	v_lshl_add_u64 v[74:75], v[64:65], 0, v[138:139]
	v_lshl_add_u64 v[70:71], v[66:67], 0, v[144:145]
	v_lshl_add_u64 v[72:73], v[66:67], 0, v[142:143]
	v_lshl_add_u64 v[78:79], v[64:65], 0, v[136:137]
	v_lshl_add_u64 v[66:67], v[66:67], 0, v[140:141]
	s_waitcnt vmcnt(0)
	v_fmamk_f32 v76, v76, 0x3a800000, v148
	v_mul_f32_e32 v77, 0x4b800000, v76
	v_cmp_gt_f32_e32 vcc, s6, v76
	s_nop 1
	v_cndmask_b32_e32 v76, v76, v77, vcc
	v_rsq_f32_e32 v80, v76
	v_lshl_add_u64 v[76:77], v[64:65], 0, v[134:135]
	v_lshl_add_u64 v[64:65], v[64:65], 0, v[112:113]
	v_mul_f32_e32 v82, 0x45800000, v80
	v_cndmask_b32_e32 v80, v80, v82, vcc
	v_pk_mul_f32 v[62:63], v[62:63], v[80:81] op_sel_hi:[1,0]
	v_pk_mul_f32 v[60:61], v[60:61], v[80:81] op_sel_hi:[1,0]
	v_pk_mul_f32 v[56:57], v[56:57], v[80:81] op_sel_hi:[1,0]
	global_store_dwordx4 v[68:69], v[60:63], off
	v_pk_mul_f32 v[58:59], v[58:59], v[80:81] op_sel_hi:[1,0]
	v_pk_mul_f32 v[52:53], v[52:53], v[80:81] op_sel_hi:[1,0]
	v_cvt_pk_bf16_f32 v60, v60, v61
	v_cvt_pk_bf16_f32 v61, v62, v63
	global_store_dwordx2 v[74:75], v[60:61], off
	global_store_dwordx4 v[70:71], v[56:59], off
	v_pk_mul_f32 v[54:55], v[54:55], v[80:81] op_sel_hi:[1,0]
	v_pk_mul_f32 v[48:49], v[48:49], v[80:81] op_sel_hi:[1,0]
	v_cvt_pk_bf16_f32 v56, v56, v57
	v_cvt_pk_bf16_f32 v57, v58, v59
	global_store_dwordx2 v[76:77], v[56:57], off
	global_store_dwordx4 v[72:73], v[52:55], off
	v_pk_mul_f32 v[50:51], v[50:51], v[80:81] op_sel_hi:[1,0]
	s_nop 0
	v_cvt_pk_bf16_f32 v52, v52, v53
	v_cvt_pk_bf16_f32 v53, v54, v55
	global_store_dwordx2 v[78:79], v[52:53], off
	global_store_dwordx4 v[66:67], v[48:51], off
	s_nop 1
	v_cvt_pk_bf16_f32 v48, v48, v49
	v_cvt_pk_bf16_f32 v49, v50, v51
	global_store_dwordx2 v[64:65], v[48:49], off
	global_load_dword v60, v[132:133], off offset:576
	v_mov_b32_e32 v49, v131
	v_add_u32_e32 v48, 0x90, v130
	v_lshlrev_b64 v[50:51], 12, v[48:49]
	v_and_or_b32 v48, v48, s7, v81
	v_ashrrev_i32_e32 v49, 31, v48
	v_lshlrev_b64 v[48:49], 9, v[48:49]
	v_lshl_add_u64 v[50:51], s[2:3], 0, v[50:51]
	v_lshl_add_u64 v[52:53], v[50:51], 0, v[146:147]
	v_lshl_add_u64 v[48:49], s[0:1], 0, v[48:49]
	v_lshl_add_u64 v[58:59], v[48:49], 0, v[138:139]
	v_lshl_add_u64 v[54:55], v[50:51], 0, v[144:145]
	v_lshl_add_u64 v[56:57], v[50:51], 0, v[142:143]
	v_lshl_add_u64 v[62:63], v[48:49], 0, v[136:137]
	v_lshl_add_u64 v[50:51], v[50:51], 0, v[140:141]
	s_waitcnt vmcnt(0)
	v_fmamk_f32 v60, v60, 0x3a800000, v148
	v_mul_f32_e32 v61, 0x4b800000, v60
	v_cmp_gt_f32_e32 vcc, s6, v60
	s_nop 1
	v_cndmask_b32_e32 v60, v60, v61, vcc
	v_rsq_f32_e32 v64, v60
	v_lshl_add_u64 v[60:61], v[48:49], 0, v[134:135]
	v_lshl_add_u64 v[48:49], v[48:49], 0, v[112:113]
	v_mul_f32_e32 v65, 0x45800000, v64
	v_cndmask_b32_e32 v64, v64, v65, vcc
	v_pk_mul_f32 v[46:47], v[46:47], v[64:65] op_sel_hi:[1,0]
	v_pk_mul_f32 v[44:45], v[44:45], v[64:65] op_sel_hi:[1,0]
	v_pk_mul_f32 v[40:41], v[40:41], v[64:65] op_sel_hi:[1,0]
	global_store_dwordx4 v[52:53], v[44:47], off
	v_pk_mul_f32 v[42:43], v[42:43], v[64:65] op_sel_hi:[1,0]
	v_pk_mul_f32 v[36:37], v[36:37], v[64:65] op_sel_hi:[1,0]
	v_cvt_pk_bf16_f32 v44, v44, v45
	v_cvt_pk_bf16_f32 v45, v46, v47
	global_store_dwordx2 v[58:59], v[44:45], off
	global_store_dwordx4 v[54:55], v[40:43], off
	v_pk_mul_f32 v[38:39], v[38:39], v[64:65] op_sel_hi:[1,0]
	v_pk_mul_f32 v[32:33], v[32:33], v[64:65] op_sel_hi:[1,0]
	v_cvt_pk_bf16_f32 v40, v40, v41
	v_cvt_pk_bf16_f32 v41, v42, v43
	global_store_dwordx2 v[60:61], v[40:41], off
	global_store_dwordx4 v[56:57], v[36:39], off
	v_pk_mul_f32 v[34:35], v[34:35], v[64:65] op_sel_hi:[1,0]
	s_nop 0
	v_cvt_pk_bf16_f32 v36, v36, v37
	v_cvt_pk_bf16_f32 v37, v38, v39
	global_store_dwordx2 v[62:63], v[36:37], off
	global_store_dwordx4 v[50:51], v[32:35], off
	s_nop 1
	v_cvt_pk_bf16_f32 v32, v32, v33
	v_cvt_pk_bf16_f32 v33, v34, v35
	global_store_dwordx2 v[48:49], v[32:33], off
	global_load_dword v44, v[132:133], off offset:640
	v_mov_b32_e32 v33, v131
	v_add_u32_e32 v32, 0xa0, v130
	v_lshlrev_b64 v[34:35], 12, v[32:33]
	v_and_or_b32 v32, v32, s8, v81
	v_ashrrev_i32_e32 v33, 31, v32
	v_lshlrev_b64 v[32:33], 9, v[32:33]
	v_lshl_add_u64 v[34:35], s[2:3], 0, v[34:35]
	v_lshl_add_u64 v[36:37], v[34:35], 0, v[146:147]
	v_lshl_add_u64 v[32:33], s[0:1], 0, v[32:33]
	v_lshl_add_u64 v[42:43], v[32:33], 0, v[138:139]
	v_lshl_add_u64 v[38:39], v[34:35], 0, v[144:145]
	v_lshl_add_u64 v[40:41], v[34:35], 0, v[142:143]
	v_lshl_add_u64 v[46:47], v[32:33], 0, v[136:137]
	v_lshl_add_u64 v[34:35], v[34:35], 0, v[140:141]
	v_add_u32_e32 v130, 0xb0, v130
	s_waitcnt vmcnt(0)
	v_fmamk_f32 v44, v44, 0x3a800000, v148
	v_mul_f32_e32 v45, 0x4b800000, v44
	v_cmp_gt_f32_e32 vcc, s6, v44
	s_nop 1
	v_cndmask_b32_e32 v44, v44, v45, vcc
	v_rsq_f32_e32 v48, v44
	v_lshl_add_u64 v[44:45], v[32:33], 0, v[134:135]
	v_lshl_add_u64 v[32:33], v[32:33], 0, v[112:113]
	v_mul_f32_e32 v49, 0x45800000, v48
	v_cndmask_b32_e32 v48, v48, v49, vcc
	v_pk_mul_f32 v[30:31], v[30:31], v[48:49] op_sel_hi:[1,0]
	v_pk_mul_f32 v[28:29], v[28:29], v[48:49] op_sel_hi:[1,0]
	v_pk_mul_f32 v[24:25], v[24:25], v[48:49] op_sel_hi:[1,0]
	global_store_dwordx4 v[36:37], v[28:31], off
	v_pk_mul_f32 v[26:27], v[26:27], v[48:49] op_sel_hi:[1,0]
	v_pk_mul_f32 v[20:21], v[20:21], v[48:49] op_sel_hi:[1,0]
	v_cvt_pk_bf16_f32 v28, v28, v29
	v_cvt_pk_bf16_f32 v29, v30, v31
	global_store_dwordx2 v[42:43], v[28:29], off
	global_store_dwordx4 v[38:39], v[24:27], off
	v_pk_mul_f32 v[22:23], v[22:23], v[48:49] op_sel_hi:[1,0]
	v_pk_mul_f32 v[16:17], v[16:17], v[48:49] op_sel_hi:[1,0]
	v_cvt_pk_bf16_f32 v24, v24, v25
	v_cvt_pk_bf16_f32 v25, v26, v27
	global_store_dwordx2 v[44:45], v[24:25], off
	global_store_dwordx4 v[40:41], v[20:23], off
	v_pk_mul_f32 v[18:19], v[18:19], v[48:49] op_sel_hi:[1,0]
	s_nop 0
	v_cvt_pk_bf16_f32 v20, v20, v21
	v_cvt_pk_bf16_f32 v21, v22, v23
	global_store_dwordx2 v[46:47], v[20:21], off
	global_store_dwordx4 v[34:35], v[16:19], off
	s_nop 1
	v_cvt_pk_bf16_f32 v16, v16, v17
	v_cvt_pk_bf16_f32 v17, v18, v19
	global_store_dwordx2 v[32:33], v[16:17], off
	global_load_dword v28, v[132:133], off offset:704
	v_and_or_b32 v18, v130, s4, v81
	v_lshlrev_b64 v[16:17], 12, v[130:131]
	v_ashrrev_i32_e32 v19, 31, v18
	v_lshlrev_b64 v[18:19], 9, v[18:19]
	v_lshl_add_u64 v[16:17], s[2:3], 0, v[16:17]
	v_lshl_add_u64 v[20:21], v[16:17], 0, v[146:147]
	v_lshl_add_u64 v[18:19], s[0:1], 0, v[18:19]
	v_lshl_add_u64 v[26:27], v[18:19], 0, v[138:139]
	v_lshl_add_u64 v[22:23], v[16:17], 0, v[144:145]
	v_lshl_add_u64 v[24:25], v[16:17], 0, v[142:143]
	v_lshl_add_u64 v[30:31], v[18:19], 0, v[136:137]
	v_lshl_add_u64 v[16:17], v[16:17], 0, v[140:141]
	s_waitcnt vmcnt(0)
	v_fmac_f32_e32 v148, 0x3a800000, v28
	v_mul_f32_e32 v28, 0x4b800000, v148
	v_cmp_gt_f32_e32 vcc, s6, v148
	s_nop 1
	v_cndmask_b32_e32 v28, v148, v28, vcc
	v_rsq_f32_e32 v32, v28
	v_lshl_add_u64 v[28:29], v[18:19], 0, v[134:135]
	v_lshl_add_u64 v[18:19], v[18:19], 0, v[112:113]
	v_mul_f32_e32 v33, 0x45800000, v32
	v_cndmask_b32_e32 v32, v32, v33, vcc
	v_pk_mul_f32 v[14:15], v[14:15], v[32:33] op_sel_hi:[1,0]
	v_pk_mul_f32 v[12:13], v[12:13], v[32:33] op_sel_hi:[1,0]
	v_pk_mul_f32 v[8:9], v[8:9], v[32:33] op_sel_hi:[1,0]
	global_store_dwordx4 v[20:21], v[12:15], off
	v_pk_mul_f32 v[10:11], v[10:11], v[32:33] op_sel_hi:[1,0]
	v_pk_mul_f32 v[4:5], v[4:5], v[32:33] op_sel_hi:[1,0]
	v_cvt_pk_bf16_f32 v12, v12, v13
	v_cvt_pk_bf16_f32 v13, v14, v15
	global_store_dwordx2 v[26:27], v[12:13], off
	global_store_dwordx4 v[22:23], v[8:11], off
	v_pk_mul_f32 v[6:7], v[6:7], v[32:33] op_sel_hi:[1,0]
	v_pk_mul_f32 v[0:1], v[0:1], v[32:33] op_sel_hi:[1,0]
	v_cvt_pk_bf16_f32 v8, v8, v9
	v_cvt_pk_bf16_f32 v9, v10, v11
	global_store_dwordx2 v[28:29], v[8:9], off
	global_store_dwordx4 v[24:25], v[4:7], off
	v_pk_mul_f32 v[2:3], v[2:3], v[32:33] op_sel_hi:[1,0]
	s_nop 0
	v_cvt_pk_bf16_f32 v4, v4, v5
	v_cvt_pk_bf16_f32 v5, v6, v7
	global_store_dwordx2 v[30:31], v[4:5], off
	global_store_dwordx4 v[16:17], v[0:3], off
	s_nop 1
	v_cvt_pk_bf16_f32 v0, v0, v1
	v_cvt_pk_bf16_f32 v1, v2, v3
	global_store_dwordx2 v[18:19], v[0:1], off
	s_waitcnt vmcnt(0)
	s_cbranch_scc0 .LBB0_440
	s_barrier

.LBB0_990:
	ds_read_b128 v[146:149], v155
	ds_read_b128 v[160:163], v155 offset:1024
	ds_read_b128 v[164:167], v155 offset:2048
	ds_read_b128 v[168:171], v155 offset:3072
	ds_read_b128 v[172:175], v156
	ds_read_b128 v[176:179], v156 offset:1024
	ds_read_b128 v[180:183], v156 offset:2048
	ds_read_b128 v[184:187], v156 offset:3072
	s_add_u32 s23, s54, 0xfffc0080
	s_addc_u32 s33, s55, -1
	s_cmp_eq_u32 s75, 12
	s_cselect_b32 s59, s20, s33
	s_cselect_b32 s58, s21, s23
	s_cselect_b32 s57, s19, s74
	s_cselect_b32 s56, s45, s73
	v_lshl_add_u64 v[220:221], s[54:55], 0, v[138:139]
	s_add_i32 m0, s51, 0xc000
	ds_read_b128 v[188:191], v157
	ds_read_b128 v[192:195], v157 offset:1024
	ds_read_b128 v[196:199], v157 offset:2048
	ds_read_b128 v[200:203], v157 offset:3072
	ds_read_b128 v[204:207], v157 offset:4096
	ds_read_b128 v[208:211], v157 offset:5120
	ds_read_b128 v[212:215], v157 offset:6144
	ds_read_b128 v[216:219], v157 offset:7168
	global_load_lds_dwordx4 v[220:221], off
	v_lshl_add_u64 v[220:221], s[54:55], 0, v[140:141]
	s_add_i32 m0, s51, 0xe000
	s_nop 0
	global_load_lds_dwordx4 v[220:221], off
	s_waitcnt vmcnt(8)
	s_waitcnt lgkmcnt(0)
	s_barrier
	s_setprio 1
	v_mfma_f32_16x16x32_bf16 v[124:127], v[146:149], v[188:191], v[124:127]
	v_mfma_f32_16x16x32_bf16 v[120:123], v[164:167], v[188:191], v[120:123]
	v_mfma_f32_16x16x32_bf16 v[108:111], v[146:149], v[196:199], v[108:111]
	v_mfma_f32_16x16x32_bf16 v[104:107], v[164:167], v[196:199], v[104:107]
	v_mfma_f32_16x16x32_bf16 v[92:95], v[146:149], v[204:207], v[92:95]
	v_mfma_f32_16x16x32_bf16 v[88:91], v[164:167], v[204:207], v[88:91]
	v_mfma_f32_16x16x32_bf16 v[76:79], v[146:149], v[212:215], v[76:79]
	v_mfma_f32_16x16x32_bf16 v[72:75], v[164:167], v[212:215], v[72:75]
	v_mfma_f32_16x16x32_bf16 v[124:127], v[160:163], v[192:195], v[124:127]
	v_mfma_f32_16x16x32_bf16 v[120:123], v[168:171], v[192:195], v[120:123]
	v_mfma_f32_16x16x32_bf16 v[108:111], v[160:163], v[200:203], v[108:111]
	v_mfma_f32_16x16x32_bf16 v[104:107], v[168:171], v[200:203], v[104:107]
	v_mfma_f32_16x16x32_bf16 v[92:95], v[160:163], v[208:211], v[92:95]
	v_mfma_f32_16x16x32_bf16 v[88:91], v[168:171], v[208:211], v[88:91]
	v_mfma_f32_16x16x32_bf16 v[76:79], v[160:163], v[216:219], v[76:79]
	v_mfma_f32_16x16x32_bf16 v[72:75], v[168:171], v[216:219], v[72:75]
	v_mfma_f32_16x16x32_bf16 v[116:119], v[172:175], v[188:191], v[116:119]
	v_mfma_f32_16x16x32_bf16 v[112:115], v[180:183], v[188:191], v[112:115]
	v_mfma_f32_16x16x32_bf16 v[100:103], v[172:175], v[196:199], v[100:103]
	v_mfma_f32_16x16x32_bf16 v[96:99], v[180:183], v[196:199], v[96:99]
	v_mfma_f32_16x16x32_bf16 v[84:87], v[172:175], v[204:207], v[84:87]
	v_mfma_f32_16x16x32_bf16 v[80:83], v[180:183], v[204:207], v[80:83]
	v_mfma_f32_16x16x32_bf16 v[68:71], v[172:175], v[212:215], v[68:71]
	v_mfma_f32_16x16x32_bf16 v[64:67], v[180:183], v[212:215], v[64:67]
	v_mfma_f32_16x16x32_bf16 v[116:119], v[176:179], v[192:195], v[116:119]
	v_mfma_f32_16x16x32_bf16 v[112:115], v[184:187], v[192:195], v[112:115]
	v_mfma_f32_16x16x32_bf16 v[100:103], v[176:179], v[200:203], v[100:103]
	v_mfma_f32_16x16x32_bf16 v[96:99], v[184:187], v[200:203], v[96:99]
	v_mfma_f32_16x16x32_bf16 v[84:87], v[176:179], v[208:211], v[84:87]
	v_mfma_f32_16x16x32_bf16 v[80:83], v[184:187], v[208:211], v[80:83]
	v_mfma_f32_16x16x32_bf16 v[68:71], v[176:179], v[216:219], v[68:71]
	v_mfma_f32_16x16x32_bf16 v[64:67], v[184:187], v[216:219], v[64:67]
	s_setprio 0
	s_barrier
	s_add_i32 s23, s71, s62
	v_lshl_add_u64 v[220:221], s[56:57], 0, v[132:133]
	s_mov_b32 m0, s23
	ds_read_b128 v[188:191], v157 offset:16384
	ds_read_b128 v[192:195], v157 offset:17408
	ds_read_b128 v[196:199], v157 offset:18432
	ds_read_b128 v[200:203], v157 offset:19456
	ds_read_b128 v[204:207], v157 offset:20480
	ds_read_b128 v[208:211], v157 offset:21504
	ds_read_b128 v[212:215], v157 offset:22528
	ds_read_b128 v[216:219], v157 offset:23552
	global_load_lds_dwordx4 v[220:221], off
	s_add_i32 m0, s23, 0x2000
	s_add_u32 s76, s56, 0x40000
	v_lshl_add_u64 v[222:223], s[56:57], 0, v[136:137]
	s_addc_u32 s77, s57, 0
	s_add_i32 s23, s72, s62
	global_load_lds_dwordx4 v[222:223], off
	v_lshl_add_u64 v[224:225], s[76:77], 0, v[132:133]
	s_mov_b32 m0, s23
	v_lshl_add_u64 v[226:227], s[58:59], 0, v[134:135]
	global_load_lds_dwordx4 v[224:225], off
	v_lshl_add_u64 v[224:225], s[76:77], 0, v[136:137]
	s_add_i32 m0, s23, 0x2000
	s_nop 0
	global_load_lds_dwordx4 v[224:225], off
	v_lshl_add_u64 v[224:225], s[58:59], 0, v[130:131]
	s_mov_b32 m0, s51
	s_nop 0
	global_load_lds_dwordx4 v[224:225], off
	s_mov_b32 m0, s53
	s_nop 0
	global_load_lds_dwordx4 v[226:227], off
	s_waitcnt vmcnt(8)
	s_waitcnt lgkmcnt(0)
	s_barrier
	s_setprio 1
	v_mfma_f32_16x16x32_bf16 v[60:63], v[146:149], v[188:191], v[60:63]
	v_mfma_f32_16x16x32_bf16 v[56:59], v[164:167], v[188:191], v[56:59]
	v_mfma_f32_16x16x32_bf16 v[44:47], v[146:149], v[196:199], v[44:47]
	v_mfma_f32_16x16x32_bf16 v[40:43], v[164:167], v[196:199], v[40:43]
	v_mfma_f32_16x16x32_bf16 v[28:31], v[146:149], v[204:207], v[28:31]
	v_mfma_f32_16x16x32_bf16 v[24:27], v[164:167], v[204:207], v[24:27]
	v_mfma_f32_16x16x32_bf16 v[12:15], v[146:149], v[212:215], v[12:15]
	v_mfma_f32_16x16x32_bf16 v[8:11], v[164:167], v[212:215], v[8:11]
	v_mfma_f32_16x16x32_bf16 v[60:63], v[160:163], v[192:195], v[60:63]
	v_mfma_f32_16x16x32_bf16 v[56:59], v[168:171], v[192:195], v[56:59]
	v_mfma_f32_16x16x32_bf16 v[44:47], v[160:163], v[200:203], v[44:47]
	v_mfma_f32_16x16x32_bf16 v[40:43], v[168:171], v[200:203], v[40:43]
	v_mfma_f32_16x16x32_bf16 v[28:31], v[160:163], v[208:211], v[28:31]
	v_mfma_f32_16x16x32_bf16 v[24:27], v[168:171], v[208:211], v[24:27]
	v_mfma_f32_16x16x32_bf16 v[12:15], v[160:163], v[216:219], v[12:15]
	v_mfma_f32_16x16x32_bf16 v[8:11], v[168:171], v[216:219], v[8:11]
	v_mfma_f32_16x16x32_bf16 v[52:55], v[172:175], v[188:191], v[52:55]
	v_mfma_f32_16x16x32_bf16 v[48:51], v[180:183], v[188:191], v[48:51]
	v_mfma_f32_16x16x32_bf16 v[36:39], v[172:175], v[196:199], v[36:39]
	v_mfma_f32_16x16x32_bf16 v[32:35], v[180:183], v[196:199], v[32:35]
	v_mfma_f32_16x16x32_bf16 v[20:23], v[172:175], v[204:207], v[20:23]
	v_mfma_f32_16x16x32_bf16 v[16:19], v[180:183], v[204:207], v[16:19]
	v_mfma_f32_16x16x32_bf16 v[4:7], v[172:175], v[212:215], v[4:7]
	v_mfma_f32_16x16x32_bf16 v[0:3], v[180:183], v[212:215], v[0:3]
	v_mfma_f32_16x16x32_bf16 v[52:55], v[176:179], v[192:195], v[52:55]
	v_mfma_f32_16x16x32_bf16 v[48:51], v[184:187], v[192:195], v[48:51]
	v_mfma_f32_16x16x32_bf16 v[36:39], v[176:179], v[200:203], v[36:39]
	v_mfma_f32_16x16x32_bf16 v[32:35], v[184:187], v[200:203], v[32:35]
	v_mfma_f32_16x16x32_bf16 v[20:23], v[176:179], v[208:211], v[20:23]
	v_mfma_f32_16x16x32_bf16 v[16:19], v[184:187], v[208:211], v[16:19]
	v_mfma_f32_16x16x32_bf16 v[4:7], v[176:179], v[216:219], v[4:7]
	v_mfma_f32_16x16x32_bf16 v[0:3], v[184:187], v[216:219], v[0:3]
	s_setprio 0
	s_barrier
	s_add_i32 s23, 0, 0x18000
	v_add_u32_e32 v159, s23, v153
	s_add_i32 s33, 0, 0x1c000
	ds_read_b128 v[146:149], v159
	ds_read_b128 v[160:163], v159 offset:1024
	ds_read_b128 v[164:167], v159 offset:2048
	ds_read_b128 v[168:171], v159 offset:3072
	v_add_u32_e32 v159, s33, v153
	ds_read_b128 v[172:175], v159
	ds_read_b128 v[176:179], v159 offset:1024
	ds_read_b128 v[180:183], v159 offset:2048
	ds_read_b128 v[184:187], v159 offset:3072
	s_add_u32 s58, s58, 0x40000
	s_addc_u32 s59, s59, 0
	s_mov_b32 m0, s63
	v_lshl_add_u64 v[228:229], s[58:59], 0, v[130:131]
	ds_read_b128 v[188:191], v157 offset:32768
	ds_read_b128 v[192:195], v157 offset:33792
	ds_read_b128 v[196:199], v157 offset:34816
	ds_read_b128 v[200:203], v157 offset:35840
	ds_read_b128 v[204:207], v157 offset:36864
	ds_read_b128 v[208:211], v157 offset:37888
	ds_read_b128 v[212:215], v157 offset:38912
	ds_read_b128 v[216:219], v157 offset:39936
	global_load_lds_dwordx4 v[228:229], off
	v_lshl_add_u64 v[228:229], s[58:59], 0, v[134:135]
	s_mov_b32 m0, s64
	s_nop 0
	global_load_lds_dwordx4 v[228:229], off
	s_waitcnt vmcnt(8)
	s_waitcnt lgkmcnt(0)
	s_barrier
	s_setprio 1
	v_mfma_f32_16x16x32_bf16 v[124:127], v[146:149], v[188:191], v[124:127]
	v_mfma_f32_16x16x32_bf16 v[120:123], v[164:167], v[188:191], v[120:123]
	v_mfma_f32_16x16x32_bf16 v[108:111], v[146:149], v[196:199], v[108:111]
	v_mfma_f32_16x16x32_bf16 v[104:107], v[164:167], v[196:199], v[104:107]
	v_mfma_f32_16x16x32_bf16 v[92:95], v[146:149], v[204:207], v[92:95]
	v_mfma_f32_16x16x32_bf16 v[88:91], v[164:167], v[204:207], v[88:91]
	v_mfma_f32_16x16x32_bf16 v[76:79], v[146:149], v[212:215], v[76:79]
	v_mfma_f32_16x16x32_bf16 v[72:75], v[164:167], v[212:215], v[72:75]
	v_mfma_f32_16x16x32_bf16 v[124:127], v[160:163], v[192:195], v[124:127]
	v_mfma_f32_16x16x32_bf16 v[120:123], v[168:171], v[192:195], v[120:123]
	v_mfma_f32_16x16x32_bf16 v[108:111], v[160:163], v[200:203], v[108:111]
	v_mfma_f32_16x16x32_bf16 v[104:107], v[168:171], v[200:203], v[104:107]
	v_mfma_f32_16x16x32_bf16 v[92:95], v[160:163], v[208:211], v[92:95]
	v_mfma_f32_16x16x32_bf16 v[88:91], v[168:171], v[208:211], v[88:91]
	v_mfma_f32_16x16x32_bf16 v[76:79], v[160:163], v[216:219], v[76:79]
	v_mfma_f32_16x16x32_bf16 v[72:75], v[168:171], v[216:219], v[72:75]
	v_mfma_f32_16x16x32_bf16 v[116:119], v[172:175], v[188:191], v[116:119]
	v_mfma_f32_16x16x32_bf16 v[112:115], v[180:183], v[188:191], v[112:115]
	v_mfma_f32_16x16x32_bf16 v[100:103], v[172:175], v[196:199], v[100:103]
	v_mfma_f32_16x16x32_bf16 v[96:99], v[180:183], v[196:199], v[96:99]
	v_mfma_f32_16x16x32_bf16 v[84:87], v[172:175], v[204:207], v[84:87]
	v_mfma_f32_16x16x32_bf16 v[80:83], v[180:183], v[204:207], v[80:83]
	v_mfma_f32_16x16x32_bf16 v[68:71], v[172:175], v[212:215], v[68:71]
	v_mfma_f32_16x16x32_bf16 v[64:67], v[180:183], v[212:215], v[64:67]
	v_mfma_f32_16x16x32_bf16 v[116:119], v[176:179], v[192:195], v[116:119]
	v_mfma_f32_16x16x32_bf16 v[112:115], v[184:187], v[192:195], v[112:115]
	v_mfma_f32_16x16x32_bf16 v[100:103], v[176:179], v[200:203], v[100:103]
	v_mfma_f32_16x16x32_bf16 v[96:99], v[184:187], v[200:203], v[96:99]
	v_mfma_f32_16x16x32_bf16 v[84:87], v[176:179], v[208:211], v[84:87]
	v_mfma_f32_16x16x32_bf16 v[80:83], v[184:187], v[208:211], v[80:83]
	v_mfma_f32_16x16x32_bf16 v[68:71], v[176:179], v[216:219], v[68:71]
	v_mfma_f32_16x16x32_bf16 v[64:67], v[184:187], v[216:219], v[64:67]
	s_setprio 0
	s_barrier
	s_add_i32 s23, s23, s62
	v_lshl_add_u64 v[220:221], v[220:221], 0, s[14:15]
	s_mov_b32 m0, s23
	ds_read_b128 v[188:191], v157 offset:49152
	ds_read_b128 v[192:195], v157 offset:50176
	ds_read_b128 v[196:199], v157 offset:51200
	ds_read_b128 v[200:203], v157 offset:52224
	ds_read_b128 v[204:207], v157 offset:53248
	ds_read_b128 v[208:211], v157 offset:54272
	ds_read_b128 v[212:215], v157 offset:55296
	ds_read_b128 v[216:219], v157 offset:56320
	global_load_lds_dwordx4 v[220:221], off
	s_add_i32 m0, s23, 0x2000
	s_add_u32 s56, s56, 0x40080
	v_lshl_add_u64 v[220:221], v[222:223], 0, s[14:15]
	s_addc_u32 s57, s57, 0
	s_add_i32 s23, s33, s62
	global_load_lds_dwordx4 v[220:221], off
	v_lshl_add_u64 v[220:221], s[56:57], 0, v[132:133]
	s_mov_b32 m0, s23
	s_nop 0
	global_load_lds_dwordx4 v[220:221], off
	v_lshl_add_u64 v[220:221], s[56:57], 0, v[136:137]
	s_add_i32 m0, s23, 0x2000
	s_nop 0
	global_load_lds_dwordx4 v[220:221], off
	v_lshl_add_u64 v[220:221], v[224:225], 0, s[14:15]
	s_mov_b32 m0, s68
	s_nop 0
	global_load_lds_dwordx4 v[220:221], off
	v_lshl_add_u64 v[220:221], v[226:227], 0, s[14:15]
	s_mov_b32 m0, s69
	s_nop 0
	global_load_lds_dwordx4 v[220:221], off
	s_waitcnt vmcnt(8)
	s_waitcnt lgkmcnt(0)
	s_barrier
	s_setprio 1
	v_mfma_f32_16x16x32_bf16 v[60:63], v[146:149], v[188:191], v[60:63]
	v_mfma_f32_16x16x32_bf16 v[56:59], v[164:167], v[188:191], v[56:59]
	v_mfma_f32_16x16x32_bf16 v[44:47], v[146:149], v[196:199], v[44:47]
	v_mfma_f32_16x16x32_bf16 v[40:43], v[164:167], v[196:199], v[40:43]
	v_mfma_f32_16x16x32_bf16 v[28:31], v[146:149], v[204:207], v[28:31]
	v_mfma_f32_16x16x32_bf16 v[24:27], v[164:167], v[204:207], v[24:27]
	v_mfma_f32_16x16x32_bf16 v[12:15], v[146:149], v[212:215], v[12:15]
	v_mfma_f32_16x16x32_bf16 v[8:11], v[164:167], v[212:215], v[8:11]
	v_mfma_f32_16x16x32_bf16 v[60:63], v[160:163], v[192:195], v[60:63]
	v_mfma_f32_16x16x32_bf16 v[56:59], v[168:171], v[192:195], v[56:59]
	v_mfma_f32_16x16x32_bf16 v[44:47], v[160:163], v[200:203], v[44:47]
	v_mfma_f32_16x16x32_bf16 v[40:43], v[168:171], v[200:203], v[40:43]
	v_mfma_f32_16x16x32_bf16 v[28:31], v[160:163], v[208:211], v[28:31]
	v_mfma_f32_16x16x32_bf16 v[24:27], v[168:171], v[208:211], v[24:27]
	v_mfma_f32_16x16x32_bf16 v[12:15], v[160:163], v[216:219], v[12:15]
	v_mfma_f32_16x16x32_bf16 v[8:11], v[168:171], v[216:219], v[8:11]
	v_mfma_f32_16x16x32_bf16 v[52:55], v[172:175], v[188:191], v[52:55]
	v_mfma_f32_16x16x32_bf16 v[48:51], v[180:183], v[188:191], v[48:51]
	v_mfma_f32_16x16x32_bf16 v[36:39], v[172:175], v[196:199], v[36:39]
	v_mfma_f32_16x16x32_bf16 v[32:35], v[180:183], v[196:199], v[32:35]
	v_mfma_f32_16x16x32_bf16 v[20:23], v[172:175], v[204:207], v[20:23]
	v_mfma_f32_16x16x32_bf16 v[16:19], v[180:183], v[204:207], v[16:19]
	v_mfma_f32_16x16x32_bf16 v[4:7], v[172:175], v[212:215], v[4:7]
	v_mfma_f32_16x16x32_bf16 v[0:3], v[180:183], v[212:215], v[0:3]
	v_mfma_f32_16x16x32_bf16 v[52:55], v[176:179], v[192:195], v[52:55]
	v_mfma_f32_16x16x32_bf16 v[48:51], v[184:187], v[192:195], v[48:51]
	v_mfma_f32_16x16x32_bf16 v[36:39], v[176:179], v[200:203], v[36:39]
	v_mfma_f32_16x16x32_bf16 v[32:35], v[184:187], v[200:203], v[32:35]
	v_mfma_f32_16x16x32_bf16 v[20:23], v[176:179], v[208:211], v[20:23]
	v_mfma_f32_16x16x32_bf16 v[16:19], v[184:187], v[208:211], v[16:19]
	v_mfma_f32_16x16x32_bf16 v[4:7], v[176:179], v[216:219], v[4:7]
	v_mfma_f32_16x16x32_bf16 v[0:3], v[184:187], v[216:219], v[0:3]
	s_setprio 0
	s_barrier
	s_add_i32 s75, s75, 2
	s_add_u32 s54, s54, 0x100
	s_addc_u32 s55, s55, 0
	s_add_u32 s73, s73, 0x100
	s_addc_u32 s74, s74, 0
	s_cmp_gt_u32 s75, 13
	s_cbranch_scc0 .LBB0_990
	s_and_b64 vcc, exec, s[16:17]
	s_cbranch_vccz .LBB0_993
	s_barrier

.LBB0_1086:
	ds_read_b128 v[146:149], v155
	ds_read_b128 v[160:163], v155 offset:1024
	ds_read_b128 v[164:167], v155 offset:2048
	ds_read_b128 v[168:171], v155 offset:3072
	ds_read_b128 v[172:175], v156
	ds_read_b128 v[176:179], v156 offset:1024
	ds_read_b128 v[180:183], v156 offset:2048
	ds_read_b128 v[184:187], v156 offset:3072
	s_add_u32 s23, s54, 0xfffc0080
	s_addc_u32 s33, s55, -1
	s_cmp_eq_u32 s82, 12
	s_cselect_b32 s59, s20, s33
	s_cselect_b32 s58, s21, s23
	s_cselect_b32 s57, s47, s81
	s_cselect_b32 s56, s49, s80
	v_lshl_add_u64 v[150:151], s[54:55], 0, v[138:139]
	s_add_i32 m0, s64, 0xc000
	ds_read_b128 v[188:191], v157
	ds_read_b128 v[192:195], v157 offset:1024
	ds_read_b128 v[196:199], v157 offset:2048
	ds_read_b128 v[200:203], v157 offset:3072
	ds_read_b128 v[204:207], v157 offset:4096
	ds_read_b128 v[208:211], v157 offset:5120
	ds_read_b128 v[212:215], v157 offset:6144
	ds_read_b128 v[216:219], v157 offset:7168
	global_load_lds_dwordx4 v[150:151], off
	v_lshl_add_u64 v[150:151], s[54:55], 0, v[140:141]
	s_add_i32 m0, s64, 0xe000
	s_nop 0
	global_load_lds_dwordx4 v[150:151], off
	s_waitcnt vmcnt(8)
	s_waitcnt lgkmcnt(0)
	s_barrier
	s_setprio 1
	v_mfma_f32_16x16x32_bf16 v[124:127], v[146:149], v[188:191], v[124:127]
	v_mfma_f32_16x16x32_bf16 v[120:123], v[164:167], v[188:191], v[120:123]
	v_mfma_f32_16x16x32_bf16 v[108:111], v[146:149], v[196:199], v[108:111]
	v_mfma_f32_16x16x32_bf16 v[104:107], v[164:167], v[196:199], v[104:107]
	v_mfma_f32_16x16x32_bf16 v[92:95], v[146:149], v[204:207], v[92:95]
	v_mfma_f32_16x16x32_bf16 v[88:91], v[164:167], v[204:207], v[88:91]
	v_mfma_f32_16x16x32_bf16 v[76:79], v[146:149], v[212:215], v[76:79]
	v_mfma_f32_16x16x32_bf16 v[72:75], v[164:167], v[212:215], v[72:75]
	v_mfma_f32_16x16x32_bf16 v[124:127], v[160:163], v[192:195], v[124:127]
	v_mfma_f32_16x16x32_bf16 v[120:123], v[168:171], v[192:195], v[120:123]
	v_mfma_f32_16x16x32_bf16 v[108:111], v[160:163], v[200:203], v[108:111]
	v_mfma_f32_16x16x32_bf16 v[104:107], v[168:171], v[200:203], v[104:107]
	v_mfma_f32_16x16x32_bf16 v[92:95], v[160:163], v[208:211], v[92:95]
	v_mfma_f32_16x16x32_bf16 v[88:91], v[168:171], v[208:211], v[88:91]
	v_mfma_f32_16x16x32_bf16 v[76:79], v[160:163], v[216:219], v[76:79]
	v_mfma_f32_16x16x32_bf16 v[72:75], v[168:171], v[216:219], v[72:75]
	v_mfma_f32_16x16x32_bf16 v[116:119], v[172:175], v[188:191], v[116:119]
	v_mfma_f32_16x16x32_bf16 v[112:115], v[180:183], v[188:191], v[112:115]
	v_mfma_f32_16x16x32_bf16 v[100:103], v[172:175], v[196:199], v[100:103]
	v_mfma_f32_16x16x32_bf16 v[96:99], v[180:183], v[196:199], v[96:99]
	v_mfma_f32_16x16x32_bf16 v[84:87], v[172:175], v[204:207], v[84:87]
	v_mfma_f32_16x16x32_bf16 v[80:83], v[180:183], v[204:207], v[80:83]
	v_mfma_f32_16x16x32_bf16 v[68:71], v[172:175], v[212:215], v[68:71]
	v_mfma_f32_16x16x32_bf16 v[64:67], v[180:183], v[212:215], v[64:67]
	v_mfma_f32_16x16x32_bf16 v[116:119], v[176:179], v[192:195], v[116:119]
	v_mfma_f32_16x16x32_bf16 v[112:115], v[184:187], v[192:195], v[112:115]
	v_mfma_f32_16x16x32_bf16 v[100:103], v[176:179], v[200:203], v[100:103]
	v_mfma_f32_16x16x32_bf16 v[96:99], v[184:187], v[200:203], v[96:99]
	v_mfma_f32_16x16x32_bf16 v[84:87], v[176:179], v[208:211], v[84:87]
	v_mfma_f32_16x16x32_bf16 v[80:83], v[184:187], v[208:211], v[80:83]
	v_mfma_f32_16x16x32_bf16 v[68:71], v[176:179], v[216:219], v[68:71]
	v_mfma_f32_16x16x32_bf16 v[64:67], v[184:187], v[216:219], v[64:67]
	s_setprio 0
	s_barrier
	s_add_i32 s23, s73, s62
	v_lshl_add_u64 v[150:151], s[56:57], 0, v[132:133]
	s_mov_b32 m0, s23
	ds_read_b128 v[188:191], v157 offset:16384
	ds_read_b128 v[192:195], v157 offset:17408
	ds_read_b128 v[196:199], v157 offset:18432
	ds_read_b128 v[200:203], v157 offset:19456
	ds_read_b128 v[204:207], v157 offset:20480
	ds_read_b128 v[208:211], v157 offset:21504
	ds_read_b128 v[212:215], v157 offset:22528
	ds_read_b128 v[216:219], v157 offset:23552
	global_load_lds_dwordx4 v[150:151], off
	s_add_i32 m0, s23, 0x2000
	s_add_u32 s84, s56, 0x40000
	v_lshl_add_u64 v[220:221], s[56:57], 0, v[136:137]
	s_addc_u32 s85, s57, 0
	s_add_i32 s23, s74, s62
	global_load_lds_dwordx4 v[220:221], off
	v_lshl_add_u64 v[222:223], s[84:85], 0, v[132:133]
	s_mov_b32 m0, s23
	v_lshl_add_u64 v[224:225], s[58:59], 0, v[134:135]
	global_load_lds_dwordx4 v[222:223], off
	v_lshl_add_u64 v[222:223], s[84:85], 0, v[136:137]
	s_add_i32 m0, s23, 0x2000
	s_nop 0
	global_load_lds_dwordx4 v[222:223], off
	v_lshl_add_u64 v[222:223], s[58:59], 0, v[130:131]
	s_mov_b32 m0, s64
	s_nop 0
	global_load_lds_dwordx4 v[222:223], off
	s_mov_b32 m0, s65
	s_nop 0
	global_load_lds_dwordx4 v[224:225], off
	s_waitcnt vmcnt(8)
	s_waitcnt lgkmcnt(0)
	s_barrier
	s_setprio 1
	v_mfma_f32_16x16x32_bf16 v[60:63], v[146:149], v[188:191], v[60:63]
	v_mfma_f32_16x16x32_bf16 v[56:59], v[164:167], v[188:191], v[56:59]
	v_mfma_f32_16x16x32_bf16 v[44:47], v[146:149], v[196:199], v[44:47]
	v_mfma_f32_16x16x32_bf16 v[40:43], v[164:167], v[196:199], v[40:43]
	v_mfma_f32_16x16x32_bf16 v[28:31], v[146:149], v[204:207], v[28:31]
	v_mfma_f32_16x16x32_bf16 v[24:27], v[164:167], v[204:207], v[24:27]
	v_mfma_f32_16x16x32_bf16 v[12:15], v[146:149], v[212:215], v[12:15]
	v_mfma_f32_16x16x32_bf16 v[8:11], v[164:167], v[212:215], v[8:11]
	v_mfma_f32_16x16x32_bf16 v[60:63], v[160:163], v[192:195], v[60:63]
	v_mfma_f32_16x16x32_bf16 v[56:59], v[168:171], v[192:195], v[56:59]
	v_mfma_f32_16x16x32_bf16 v[44:47], v[160:163], v[200:203], v[44:47]
	v_mfma_f32_16x16x32_bf16 v[40:43], v[168:171], v[200:203], v[40:43]
	v_mfma_f32_16x16x32_bf16 v[28:31], v[160:163], v[208:211], v[28:31]
	v_mfma_f32_16x16x32_bf16 v[24:27], v[168:171], v[208:211], v[24:27]
	v_mfma_f32_16x16x32_bf16 v[12:15], v[160:163], v[216:219], v[12:15]
	v_mfma_f32_16x16x32_bf16 v[8:11], v[168:171], v[216:219], v[8:11]
	v_mfma_f32_16x16x32_bf16 v[52:55], v[172:175], v[188:191], v[52:55]
	v_mfma_f32_16x16x32_bf16 v[48:51], v[180:183], v[188:191], v[48:51]
	v_mfma_f32_16x16x32_bf16 v[36:39], v[172:175], v[196:199], v[36:39]
	v_mfma_f32_16x16x32_bf16 v[32:35], v[180:183], v[196:199], v[32:35]
	v_mfma_f32_16x16x32_bf16 v[20:23], v[172:175], v[204:207], v[20:23]
	v_mfma_f32_16x16x32_bf16 v[16:19], v[180:183], v[204:207], v[16:19]
	v_mfma_f32_16x16x32_bf16 v[4:7], v[172:175], v[212:215], v[4:7]
	v_mfma_f32_16x16x32_bf16 v[0:3], v[180:183], v[212:215], v[0:3]
	v_mfma_f32_16x16x32_bf16 v[52:55], v[176:179], v[192:195], v[52:55]
	v_mfma_f32_16x16x32_bf16 v[48:51], v[184:187], v[192:195], v[48:51]
	v_mfma_f32_16x16x32_bf16 v[36:39], v[176:179], v[200:203], v[36:39]
	v_mfma_f32_16x16x32_bf16 v[32:35], v[184:187], v[200:203], v[32:35]
	v_mfma_f32_16x16x32_bf16 v[20:23], v[176:179], v[208:211], v[20:23]
	v_mfma_f32_16x16x32_bf16 v[16:19], v[184:187], v[208:211], v[16:19]
	v_mfma_f32_16x16x32_bf16 v[4:7], v[176:179], v[216:219], v[4:7]
	v_mfma_f32_16x16x32_bf16 v[0:3], v[184:187], v[216:219], v[0:3]
	s_setprio 0
	s_barrier
	s_add_i32 s23, 0, 0x18000
	v_add_u32_e32 v159, s23, v153
	s_add_i32 s33, 0, 0x1c000
	ds_read_b128 v[146:149], v159
	ds_read_b128 v[160:163], v159 offset:1024
	ds_read_b128 v[164:167], v159 offset:2048
	ds_read_b128 v[168:171], v159 offset:3072
	v_add_u32_e32 v159, s33, v153
	ds_read_b128 v[172:175], v159
	ds_read_b128 v[176:179], v159 offset:1024
	ds_read_b128 v[180:183], v159 offset:2048
	ds_read_b128 v[184:187], v159 offset:3072
	s_add_u32 s58, s58, 0x40000
	s_addc_u32 s59, s59, 0
	s_mov_b32 m0, s66
	v_lshl_add_u64 v[226:227], s[58:59], 0, v[130:131]
	ds_read_b128 v[188:191], v157 offset:32768
	ds_read_b128 v[192:195], v157 offset:33792
	ds_read_b128 v[196:199], v157 offset:34816
	ds_read_b128 v[200:203], v157 offset:35840
	ds_read_b128 v[204:207], v157 offset:36864
	ds_read_b128 v[208:211], v157 offset:37888
	ds_read_b128 v[212:215], v157 offset:38912
	ds_read_b128 v[216:219], v157 offset:39936
	global_load_lds_dwordx4 v[226:227], off
	v_lshl_add_u64 v[226:227], s[58:59], 0, v[134:135]
	s_mov_b32 m0, s67
	s_nop 0
	global_load_lds_dwordx4 v[226:227], off
	s_waitcnt vmcnt(8)
	s_waitcnt lgkmcnt(0)
	s_barrier
	s_setprio 1
	v_mfma_f32_16x16x32_bf16 v[124:127], v[146:149], v[188:191], v[124:127]
	v_mfma_f32_16x16x32_bf16 v[120:123], v[164:167], v[188:191], v[120:123]
	v_mfma_f32_16x16x32_bf16 v[108:111], v[146:149], v[196:199], v[108:111]
	v_mfma_f32_16x16x32_bf16 v[104:107], v[164:167], v[196:199], v[104:107]
	v_mfma_f32_16x16x32_bf16 v[92:95], v[146:149], v[204:207], v[92:95]
	v_mfma_f32_16x16x32_bf16 v[88:91], v[164:167], v[204:207], v[88:91]
	v_mfma_f32_16x16x32_bf16 v[76:79], v[146:149], v[212:215], v[76:79]
	v_mfma_f32_16x16x32_bf16 v[72:75], v[164:167], v[212:215], v[72:75]
	v_mfma_f32_16x16x32_bf16 v[124:127], v[160:163], v[192:195], v[124:127]
	v_mfma_f32_16x16x32_bf16 v[120:123], v[168:171], v[192:195], v[120:123]
	v_mfma_f32_16x16x32_bf16 v[108:111], v[160:163], v[200:203], v[108:111]
	v_mfma_f32_16x16x32_bf16 v[104:107], v[168:171], v[200:203], v[104:107]
	v_mfma_f32_16x16x32_bf16 v[92:95], v[160:163], v[208:211], v[92:95]
	v_mfma_f32_16x16x32_bf16 v[88:91], v[168:171], v[208:211], v[88:91]
	v_mfma_f32_16x16x32_bf16 v[76:79], v[160:163], v[216:219], v[76:79]
	v_mfma_f32_16x16x32_bf16 v[72:75], v[168:171], v[216:219], v[72:75]
	v_mfma_f32_16x16x32_bf16 v[116:119], v[172:175], v[188:191], v[116:119]
	v_mfma_f32_16x16x32_bf16 v[112:115], v[180:183], v[188:191], v[112:115]
	v_mfma_f32_16x16x32_bf16 v[100:103], v[172:175], v[196:199], v[100:103]
	v_mfma_f32_16x16x32_bf16 v[96:99], v[180:183], v[196:199], v[96:99]
	v_mfma_f32_16x16x32_bf16 v[84:87], v[172:175], v[204:207], v[84:87]
	v_mfma_f32_16x16x32_bf16 v[80:83], v[180:183], v[204:207], v[80:83]
	v_mfma_f32_16x16x32_bf16 v[68:71], v[172:175], v[212:215], v[68:71]
	v_mfma_f32_16x16x32_bf16 v[64:67], v[180:183], v[212:215], v[64:67]
	v_mfma_f32_16x16x32_bf16 v[116:119], v[176:179], v[192:195], v[116:119]
	v_mfma_f32_16x16x32_bf16 v[112:115], v[184:187], v[192:195], v[112:115]
	v_mfma_f32_16x16x32_bf16 v[100:103], v[176:179], v[200:203], v[100:103]
	v_mfma_f32_16x16x32_bf16 v[96:99], v[184:187], v[200:203], v[96:99]
	v_mfma_f32_16x16x32_bf16 v[84:87], v[176:179], v[208:211], v[84:87]
	v_mfma_f32_16x16x32_bf16 v[80:83], v[184:187], v[208:211], v[80:83]
	v_mfma_f32_16x16x32_bf16 v[68:71], v[176:179], v[216:219], v[68:71]
	v_mfma_f32_16x16x32_bf16 v[64:67], v[184:187], v[216:219], v[64:67]
	s_setprio 0
	s_barrier
	s_add_i32 s23, s23, s62
	v_lshl_add_u64 v[150:151], v[150:151], 0, s[16:17]
	s_mov_b32 m0, s23
	ds_read_b128 v[188:191], v157 offset:49152
	ds_read_b128 v[192:195], v157 offset:50176
	ds_read_b128 v[196:199], v157 offset:51200
	ds_read_b128 v[200:203], v157 offset:52224
	ds_read_b128 v[204:207], v157 offset:53248
	ds_read_b128 v[208:211], v157 offset:54272
	ds_read_b128 v[212:215], v157 offset:55296
	ds_read_b128 v[216:219], v157 offset:56320
	global_load_lds_dwordx4 v[150:151], off
	s_add_i32 m0, s23, 0x2000
	s_add_u32 s56, s56, 0x40080
	v_lshl_add_u64 v[150:151], v[220:221], 0, s[16:17]
	s_addc_u32 s57, s57, 0
	s_add_i32 s23, s33, s62
	global_load_lds_dwordx4 v[150:151], off
	v_lshl_add_u64 v[150:151], s[56:57], 0, v[132:133]
	s_mov_b32 m0, s23
	s_nop 0
	global_load_lds_dwordx4 v[150:151], off
	v_lshl_add_u64 v[150:151], s[56:57], 0, v[136:137]
	s_add_i32 m0, s23, 0x2000
	s_nop 0
	global_load_lds_dwordx4 v[150:151], off
	v_lshl_add_u64 v[150:151], v[222:223], 0, s[16:17]
	s_mov_b32 m0, s70
	s_nop 0
	global_load_lds_dwordx4 v[150:151], off
	v_lshl_add_u64 v[150:151], v[224:225], 0, s[16:17]
	s_mov_b32 m0, s71
	s_nop 0
	global_load_lds_dwordx4 v[150:151], off
	s_waitcnt vmcnt(8)
	s_waitcnt lgkmcnt(0)
	s_barrier
	s_setprio 1
	v_mfma_f32_16x16x32_bf16 v[60:63], v[146:149], v[188:191], v[60:63]
	v_mfma_f32_16x16x32_bf16 v[56:59], v[164:167], v[188:191], v[56:59]
	v_mfma_f32_16x16x32_bf16 v[44:47], v[146:149], v[196:199], v[44:47]
	v_mfma_f32_16x16x32_bf16 v[40:43], v[164:167], v[196:199], v[40:43]
	v_mfma_f32_16x16x32_bf16 v[28:31], v[146:149], v[204:207], v[28:31]
	v_mfma_f32_16x16x32_bf16 v[24:27], v[164:167], v[204:207], v[24:27]
	v_mfma_f32_16x16x32_bf16 v[12:15], v[146:149], v[212:215], v[12:15]
	v_mfma_f32_16x16x32_bf16 v[8:11], v[164:167], v[212:215], v[8:11]
	v_mfma_f32_16x16x32_bf16 v[60:63], v[160:163], v[192:195], v[60:63]
	v_mfma_f32_16x16x32_bf16 v[56:59], v[168:171], v[192:195], v[56:59]
	v_mfma_f32_16x16x32_bf16 v[44:47], v[160:163], v[200:203], v[44:47]
	v_mfma_f32_16x16x32_bf16 v[40:43], v[168:171], v[200:203], v[40:43]
	v_mfma_f32_16x16x32_bf16 v[28:31], v[160:163], v[208:211], v[28:31]
	v_mfma_f32_16x16x32_bf16 v[24:27], v[168:171], v[208:211], v[24:27]
	v_mfma_f32_16x16x32_bf16 v[12:15], v[160:163], v[216:219], v[12:15]
	v_mfma_f32_16x16x32_bf16 v[8:11], v[168:171], v[216:219], v[8:11]
	v_mfma_f32_16x16x32_bf16 v[52:55], v[172:175], v[188:191], v[52:55]
	v_mfma_f32_16x16x32_bf16 v[48:51], v[180:183], v[188:191], v[48:51]
	v_mfma_f32_16x16x32_bf16 v[36:39], v[172:175], v[196:199], v[36:39]
	v_mfma_f32_16x16x32_bf16 v[32:35], v[180:183], v[196:199], v[32:35]
	v_mfma_f32_16x16x32_bf16 v[20:23], v[172:175], v[204:207], v[20:23]
	v_mfma_f32_16x16x32_bf16 v[16:19], v[180:183], v[204:207], v[16:19]
	v_mfma_f32_16x16x32_bf16 v[4:7], v[172:175], v[212:215], v[4:7]
	v_mfma_f32_16x16x32_bf16 v[0:3], v[180:183], v[212:215], v[0:3]
	v_mfma_f32_16x16x32_bf16 v[52:55], v[176:179], v[192:195], v[52:55]
	v_mfma_f32_16x16x32_bf16 v[48:51], v[184:187], v[192:195], v[48:51]
	v_mfma_f32_16x16x32_bf16 v[36:39], v[176:179], v[200:203], v[36:39]
	v_mfma_f32_16x16x32_bf16 v[32:35], v[184:187], v[200:203], v[32:35]
	v_mfma_f32_16x16x32_bf16 v[20:23], v[176:179], v[208:211], v[20:23]
	v_mfma_f32_16x16x32_bf16 v[16:19], v[184:187], v[208:211], v[16:19]
	v_mfma_f32_16x16x32_bf16 v[4:7], v[176:179], v[216:219], v[4:7]
	v_mfma_f32_16x16x32_bf16 v[0:3], v[184:187], v[216:219], v[0:3]
	s_setprio 0
	s_barrier
	s_add_i32 s82, s82, 2
	s_add_u32 s54, s54, 0x100
	s_addc_u32 s55, s55, 0
	s_add_u32 s80, s80, 0x100
	s_addc_u32 s81, s81, 0
	s_cmp_gt_u32 s82, 13
	s_cbranch_scc0 .LBB0_1086
	s_and_b64 vcc, exec, s[18:19]
	s_cbranch_vccz .LBB0_1089
	s_barrier

.LBB0_1246:
	ds_read_b128 v[146:149], v155
	ds_read_b128 v[160:163], v155 offset:1024
	ds_read_b128 v[164:167], v155 offset:2048
	ds_read_b128 v[168:171], v155 offset:3072
	ds_read_b128 v[172:175], v156
	ds_read_b128 v[176:179], v156 offset:1024
	ds_read_b128 v[180:183], v156 offset:2048
	ds_read_b128 v[184:187], v156 offset:3072
	s_add_u32 s23, s46, 0xfffc0080
	s_addc_u32 s33, s47, -1
	s_cmp_eq_u32 s67, 12
	s_cselect_b32 s51, s20, s33
	s_cselect_b32 s50, s21, s23
	s_cselect_b32 s49, s19, s66
	s_cselect_b32 s48, s37, s65
	v_lshl_add_u64 v[220:221], s[46:47], 0, v[138:139]
	s_add_i32 m0, s43, 0xc000
	ds_read_b128 v[188:191], v157
	ds_read_b128 v[192:195], v157 offset:1024
	ds_read_b128 v[196:199], v157 offset:2048
	ds_read_b128 v[200:203], v157 offset:3072
	ds_read_b128 v[204:207], v157 offset:4096
	ds_read_b128 v[208:211], v157 offset:5120
	ds_read_b128 v[212:215], v157 offset:6144
	ds_read_b128 v[216:219], v157 offset:7168
	global_load_lds_dwordx4 v[220:221], off
	v_lshl_add_u64 v[220:221], s[46:47], 0, v[140:141]
	s_add_i32 m0, s43, 0xe000
	s_nop 0
	global_load_lds_dwordx4 v[220:221], off
	s_waitcnt vmcnt(8)
	s_waitcnt lgkmcnt(0)
	s_barrier
	s_setprio 1
	v_mfma_f32_16x16x32_bf16 v[124:127], v[146:149], v[188:191], v[124:127]
	v_mfma_f32_16x16x32_bf16 v[120:123], v[164:167], v[188:191], v[120:123]
	v_mfma_f32_16x16x32_bf16 v[108:111], v[146:149], v[196:199], v[108:111]
	v_mfma_f32_16x16x32_bf16 v[104:107], v[164:167], v[196:199], v[104:107]
	v_mfma_f32_16x16x32_bf16 v[92:95], v[146:149], v[204:207], v[92:95]
	v_mfma_f32_16x16x32_bf16 v[88:91], v[164:167], v[204:207], v[88:91]
	v_mfma_f32_16x16x32_bf16 v[76:79], v[146:149], v[212:215], v[76:79]
	v_mfma_f32_16x16x32_bf16 v[72:75], v[164:167], v[212:215], v[72:75]
	v_mfma_f32_16x16x32_bf16 v[124:127], v[160:163], v[192:195], v[124:127]
	v_mfma_f32_16x16x32_bf16 v[120:123], v[168:171], v[192:195], v[120:123]
	v_mfma_f32_16x16x32_bf16 v[108:111], v[160:163], v[200:203], v[108:111]
	v_mfma_f32_16x16x32_bf16 v[104:107], v[168:171], v[200:203], v[104:107]
	v_mfma_f32_16x16x32_bf16 v[92:95], v[160:163], v[208:211], v[92:95]
	v_mfma_f32_16x16x32_bf16 v[88:91], v[168:171], v[208:211], v[88:91]
	v_mfma_f32_16x16x32_bf16 v[76:79], v[160:163], v[216:219], v[76:79]
	v_mfma_f32_16x16x32_bf16 v[72:75], v[168:171], v[216:219], v[72:75]
	v_mfma_f32_16x16x32_bf16 v[116:119], v[172:175], v[188:191], v[116:119]
	v_mfma_f32_16x16x32_bf16 v[112:115], v[180:183], v[188:191], v[112:115]
	v_mfma_f32_16x16x32_bf16 v[100:103], v[172:175], v[196:199], v[100:103]
	v_mfma_f32_16x16x32_bf16 v[96:99], v[180:183], v[196:199], v[96:99]
	v_mfma_f32_16x16x32_bf16 v[84:87], v[172:175], v[204:207], v[84:87]
	v_mfma_f32_16x16x32_bf16 v[80:83], v[180:183], v[204:207], v[80:83]
	v_mfma_f32_16x16x32_bf16 v[68:71], v[172:175], v[212:215], v[68:71]
	v_mfma_f32_16x16x32_bf16 v[64:67], v[180:183], v[212:215], v[64:67]
	v_mfma_f32_16x16x32_bf16 v[116:119], v[176:179], v[192:195], v[116:119]
	v_mfma_f32_16x16x32_bf16 v[112:115], v[184:187], v[192:195], v[112:115]
	v_mfma_f32_16x16x32_bf16 v[100:103], v[176:179], v[200:203], v[100:103]
	v_mfma_f32_16x16x32_bf16 v[96:99], v[184:187], v[200:203], v[96:99]
	v_mfma_f32_16x16x32_bf16 v[84:87], v[176:179], v[208:211], v[84:87]
	v_mfma_f32_16x16x32_bf16 v[80:83], v[184:187], v[208:211], v[80:83]
	v_mfma_f32_16x16x32_bf16 v[68:71], v[176:179], v[216:219], v[68:71]
	v_mfma_f32_16x16x32_bf16 v[64:67], v[184:187], v[216:219], v[64:67]
	s_setprio 0
	s_barrier
	s_add_i32 s23, s63, s54
	v_lshl_add_u64 v[220:221], s[48:49], 0, v[132:133]
	s_mov_b32 m0, s23
	ds_read_b128 v[188:191], v157 offset:16384
	ds_read_b128 v[192:195], v157 offset:17408
	ds_read_b128 v[196:199], v157 offset:18432
	ds_read_b128 v[200:203], v157 offset:19456
	ds_read_b128 v[204:207], v157 offset:20480
	ds_read_b128 v[208:211], v157 offset:21504
	ds_read_b128 v[212:215], v157 offset:22528
	ds_read_b128 v[216:219], v157 offset:23552
	global_load_lds_dwordx4 v[220:221], off
	s_add_i32 m0, s23, 0x2000
	s_add_u32 s68, s48, 0x40000
	v_lshl_add_u64 v[222:223], s[48:49], 0, v[136:137]
	s_addc_u32 s69, s49, 0
	s_add_i32 s23, s64, s54
	global_load_lds_dwordx4 v[222:223], off
	v_lshl_add_u64 v[224:225], s[68:69], 0, v[132:133]
	s_mov_b32 m0, s23
	v_lshl_add_u64 v[226:227], s[50:51], 0, v[134:135]
	global_load_lds_dwordx4 v[224:225], off
	v_lshl_add_u64 v[224:225], s[68:69], 0, v[136:137]
	s_add_i32 m0, s23, 0x2000
	s_nop 0
	global_load_lds_dwordx4 v[224:225], off
	v_lshl_add_u64 v[224:225], s[50:51], 0, v[130:131]
	s_mov_b32 m0, s43
	s_nop 0
	global_load_lds_dwordx4 v[224:225], off
	s_mov_b32 m0, s45
	s_nop 0
	global_load_lds_dwordx4 v[226:227], off
	s_waitcnt vmcnt(8)
	s_waitcnt lgkmcnt(0)
	s_barrier
	s_setprio 1
	v_mfma_f32_16x16x32_bf16 v[60:63], v[146:149], v[188:191], v[60:63]
	v_mfma_f32_16x16x32_bf16 v[56:59], v[164:167], v[188:191], v[56:59]
	v_mfma_f32_16x16x32_bf16 v[44:47], v[146:149], v[196:199], v[44:47]
	v_mfma_f32_16x16x32_bf16 v[40:43], v[164:167], v[196:199], v[40:43]
	v_mfma_f32_16x16x32_bf16 v[28:31], v[146:149], v[204:207], v[28:31]
	v_mfma_f32_16x16x32_bf16 v[24:27], v[164:167], v[204:207], v[24:27]
	v_mfma_f32_16x16x32_bf16 v[12:15], v[146:149], v[212:215], v[12:15]
	v_mfma_f32_16x16x32_bf16 v[8:11], v[164:167], v[212:215], v[8:11]
	v_mfma_f32_16x16x32_bf16 v[60:63], v[160:163], v[192:195], v[60:63]
	v_mfma_f32_16x16x32_bf16 v[56:59], v[168:171], v[192:195], v[56:59]
	v_mfma_f32_16x16x32_bf16 v[44:47], v[160:163], v[200:203], v[44:47]
	v_mfma_f32_16x16x32_bf16 v[40:43], v[168:171], v[200:203], v[40:43]
	v_mfma_f32_16x16x32_bf16 v[28:31], v[160:163], v[208:211], v[28:31]
	v_mfma_f32_16x16x32_bf16 v[24:27], v[168:171], v[208:211], v[24:27]
	v_mfma_f32_16x16x32_bf16 v[12:15], v[160:163], v[216:219], v[12:15]
	v_mfma_f32_16x16x32_bf16 v[8:11], v[168:171], v[216:219], v[8:11]
	v_mfma_f32_16x16x32_bf16 v[52:55], v[172:175], v[188:191], v[52:55]
	v_mfma_f32_16x16x32_bf16 v[48:51], v[180:183], v[188:191], v[48:51]
	v_mfma_f32_16x16x32_bf16 v[36:39], v[172:175], v[196:199], v[36:39]
	v_mfma_f32_16x16x32_bf16 v[32:35], v[180:183], v[196:199], v[32:35]
	v_mfma_f32_16x16x32_bf16 v[20:23], v[172:175], v[204:207], v[20:23]
	v_mfma_f32_16x16x32_bf16 v[16:19], v[180:183], v[204:207], v[16:19]
	v_mfma_f32_16x16x32_bf16 v[4:7], v[172:175], v[212:215], v[4:7]
	v_mfma_f32_16x16x32_bf16 v[0:3], v[180:183], v[212:215], v[0:3]
	v_mfma_f32_16x16x32_bf16 v[52:55], v[176:179], v[192:195], v[52:55]
	v_mfma_f32_16x16x32_bf16 v[48:51], v[184:187], v[192:195], v[48:51]
	v_mfma_f32_16x16x32_bf16 v[36:39], v[176:179], v[200:203], v[36:39]
	v_mfma_f32_16x16x32_bf16 v[32:35], v[184:187], v[200:203], v[32:35]
	v_mfma_f32_16x16x32_bf16 v[20:23], v[176:179], v[208:211], v[20:23]
	v_mfma_f32_16x16x32_bf16 v[16:19], v[184:187], v[208:211], v[16:19]
	v_mfma_f32_16x16x32_bf16 v[4:7], v[176:179], v[216:219], v[4:7]
	v_mfma_f32_16x16x32_bf16 v[0:3], v[184:187], v[216:219], v[0:3]
	s_setprio 0
	s_barrier
	s_add_i32 s23, 0, 0x18000
	v_add_u32_e32 v159, s23, v153
	s_add_i32 s33, 0, 0x1c000
	ds_read_b128 v[146:149], v159
	ds_read_b128 v[160:163], v159 offset:1024
	ds_read_b128 v[164:167], v159 offset:2048
	ds_read_b128 v[168:171], v159 offset:3072
	v_add_u32_e32 v159, s33, v153
	ds_read_b128 v[172:175], v159
	ds_read_b128 v[176:179], v159 offset:1024
	ds_read_b128 v[180:183], v159 offset:2048
	ds_read_b128 v[184:187], v159 offset:3072
	s_add_u32 s50, s50, 0x40000
	s_addc_u32 s51, s51, 0
	s_mov_b32 m0, s55
	v_lshl_add_u64 v[228:229], s[50:51], 0, v[130:131]
	ds_read_b128 v[188:191], v157 offset:32768
	ds_read_b128 v[192:195], v157 offset:33792
	ds_read_b128 v[196:199], v157 offset:34816
	ds_read_b128 v[200:203], v157 offset:35840
	ds_read_b128 v[204:207], v157 offset:36864
	ds_read_b128 v[208:211], v157 offset:37888
	ds_read_b128 v[212:215], v157 offset:38912
	ds_read_b128 v[216:219], v157 offset:39936
	global_load_lds_dwordx4 v[228:229], off
	v_lshl_add_u64 v[228:229], s[50:51], 0, v[134:135]
	s_mov_b32 m0, s56
	s_nop 0
	global_load_lds_dwordx4 v[228:229], off
	s_waitcnt vmcnt(8)
	s_waitcnt lgkmcnt(0)
	s_barrier
	s_setprio 1
	v_mfma_f32_16x16x32_bf16 v[124:127], v[146:149], v[188:191], v[124:127]
	v_mfma_f32_16x16x32_bf16 v[120:123], v[164:167], v[188:191], v[120:123]
	v_mfma_f32_16x16x32_bf16 v[108:111], v[146:149], v[196:199], v[108:111]
	v_mfma_f32_16x16x32_bf16 v[104:107], v[164:167], v[196:199], v[104:107]
	v_mfma_f32_16x16x32_bf16 v[92:95], v[146:149], v[204:207], v[92:95]
	v_mfma_f32_16x16x32_bf16 v[88:91], v[164:167], v[204:207], v[88:91]
	v_mfma_f32_16x16x32_bf16 v[76:79], v[146:149], v[212:215], v[76:79]
	v_mfma_f32_16x16x32_bf16 v[72:75], v[164:167], v[212:215], v[72:75]
	v_mfma_f32_16x16x32_bf16 v[124:127], v[160:163], v[192:195], v[124:127]
	v_mfma_f32_16x16x32_bf16 v[120:123], v[168:171], v[192:195], v[120:123]
	v_mfma_f32_16x16x32_bf16 v[108:111], v[160:163], v[200:203], v[108:111]
	v_mfma_f32_16x16x32_bf16 v[104:107], v[168:171], v[200:203], v[104:107]
	v_mfma_f32_16x16x32_bf16 v[92:95], v[160:163], v[208:211], v[92:95]
	v_mfma_f32_16x16x32_bf16 v[88:91], v[168:171], v[208:211], v[88:91]
	v_mfma_f32_16x16x32_bf16 v[76:79], v[160:163], v[216:219], v[76:79]
	v_mfma_f32_16x16x32_bf16 v[72:75], v[168:171], v[216:219], v[72:75]
	v_mfma_f32_16x16x32_bf16 v[116:119], v[172:175], v[188:191], v[116:119]
	v_mfma_f32_16x16x32_bf16 v[112:115], v[180:183], v[188:191], v[112:115]
	v_mfma_f32_16x16x32_bf16 v[100:103], v[172:175], v[196:199], v[100:103]
	v_mfma_f32_16x16x32_bf16 v[96:99], v[180:183], v[196:199], v[96:99]
	v_mfma_f32_16x16x32_bf16 v[84:87], v[172:175], v[204:207], v[84:87]
	v_mfma_f32_16x16x32_bf16 v[80:83], v[180:183], v[204:207], v[80:83]
	v_mfma_f32_16x16x32_bf16 v[68:71], v[172:175], v[212:215], v[68:71]
	v_mfma_f32_16x16x32_bf16 v[64:67], v[180:183], v[212:215], v[64:67]
	v_mfma_f32_16x16x32_bf16 v[116:119], v[176:179], v[192:195], v[116:119]
	v_mfma_f32_16x16x32_bf16 v[112:115], v[184:187], v[192:195], v[112:115]
	v_mfma_f32_16x16x32_bf16 v[100:103], v[176:179], v[200:203], v[100:103]
	v_mfma_f32_16x16x32_bf16 v[96:99], v[184:187], v[200:203], v[96:99]
	v_mfma_f32_16x16x32_bf16 v[84:87], v[176:179], v[208:211], v[84:87]
	v_mfma_f32_16x16x32_bf16 v[80:83], v[184:187], v[208:211], v[80:83]
	v_mfma_f32_16x16x32_bf16 v[68:71], v[176:179], v[216:219], v[68:71]
	v_mfma_f32_16x16x32_bf16 v[64:67], v[184:187], v[216:219], v[64:67]
	s_setprio 0
	s_barrier
	s_add_i32 s23, s23, s54
	v_lshl_add_u64 v[220:221], v[220:221], 0, s[14:15]
	s_mov_b32 m0, s23
	ds_read_b128 v[188:191], v157 offset:49152
	ds_read_b128 v[192:195], v157 offset:50176
	ds_read_b128 v[196:199], v157 offset:51200
	ds_read_b128 v[200:203], v157 offset:52224
	ds_read_b128 v[204:207], v157 offset:53248
	ds_read_b128 v[208:211], v157 offset:54272
	ds_read_b128 v[212:215], v157 offset:55296
	ds_read_b128 v[216:219], v157 offset:56320
	global_load_lds_dwordx4 v[220:221], off
	s_add_i32 m0, s23, 0x2000
	s_add_u32 s48, s48, 0x40080
	v_lshl_add_u64 v[220:221], v[222:223], 0, s[14:15]
	s_addc_u32 s49, s49, 0
	s_add_i32 s23, s33, s54
	global_load_lds_dwordx4 v[220:221], off
	v_lshl_add_u64 v[220:221], s[48:49], 0, v[132:133]
	s_mov_b32 m0, s23
	s_nop 0
	global_load_lds_dwordx4 v[220:221], off
	v_lshl_add_u64 v[220:221], s[48:49], 0, v[136:137]
	s_add_i32 m0, s23, 0x2000
	s_nop 0
	global_load_lds_dwordx4 v[220:221], off
	v_lshl_add_u64 v[220:221], v[224:225], 0, s[14:15]
	s_mov_b32 m0, s60
	s_nop 0
	global_load_lds_dwordx4 v[220:221], off
	v_lshl_add_u64 v[220:221], v[226:227], 0, s[14:15]
	s_mov_b32 m0, s61
	s_nop 0
	global_load_lds_dwordx4 v[220:221], off
	s_waitcnt vmcnt(8)
	s_waitcnt lgkmcnt(0)
	s_barrier
	s_setprio 1
	v_mfma_f32_16x16x32_bf16 v[60:63], v[146:149], v[188:191], v[60:63]
	v_mfma_f32_16x16x32_bf16 v[56:59], v[164:167], v[188:191], v[56:59]
	v_mfma_f32_16x16x32_bf16 v[44:47], v[146:149], v[196:199], v[44:47]
	v_mfma_f32_16x16x32_bf16 v[40:43], v[164:167], v[196:199], v[40:43]
	v_mfma_f32_16x16x32_bf16 v[28:31], v[146:149], v[204:207], v[28:31]
	v_mfma_f32_16x16x32_bf16 v[24:27], v[164:167], v[204:207], v[24:27]
	v_mfma_f32_16x16x32_bf16 v[12:15], v[146:149], v[212:215], v[12:15]
	v_mfma_f32_16x16x32_bf16 v[8:11], v[164:167], v[212:215], v[8:11]
	v_mfma_f32_16x16x32_bf16 v[60:63], v[160:163], v[192:195], v[60:63]
	v_mfma_f32_16x16x32_bf16 v[56:59], v[168:171], v[192:195], v[56:59]
	v_mfma_f32_16x16x32_bf16 v[44:47], v[160:163], v[200:203], v[44:47]
	v_mfma_f32_16x16x32_bf16 v[40:43], v[168:171], v[200:203], v[40:43]
	v_mfma_f32_16x16x32_bf16 v[28:31], v[160:163], v[208:211], v[28:31]
	v_mfma_f32_16x16x32_bf16 v[24:27], v[168:171], v[208:211], v[24:27]
	v_mfma_f32_16x16x32_bf16 v[12:15], v[160:163], v[216:219], v[12:15]
	v_mfma_f32_16x16x32_bf16 v[8:11], v[168:171], v[216:219], v[8:11]
	v_mfma_f32_16x16x32_bf16 v[52:55], v[172:175], v[188:191], v[52:55]
	v_mfma_f32_16x16x32_bf16 v[48:51], v[180:183], v[188:191], v[48:51]
	v_mfma_f32_16x16x32_bf16 v[36:39], v[172:175], v[196:199], v[36:39]
	v_mfma_f32_16x16x32_bf16 v[32:35], v[180:183], v[196:199], v[32:35]
	v_mfma_f32_16x16x32_bf16 v[20:23], v[172:175], v[204:207], v[20:23]
	v_mfma_f32_16x16x32_bf16 v[16:19], v[180:183], v[204:207], v[16:19]
	v_mfma_f32_16x16x32_bf16 v[4:7], v[172:175], v[212:215], v[4:7]
	v_mfma_f32_16x16x32_bf16 v[0:3], v[180:183], v[212:215], v[0:3]
	v_mfma_f32_16x16x32_bf16 v[52:55], v[176:179], v[192:195], v[52:55]
	v_mfma_f32_16x16x32_bf16 v[48:51], v[184:187], v[192:195], v[48:51]
	v_mfma_f32_16x16x32_bf16 v[36:39], v[176:179], v[200:203], v[36:39]
	v_mfma_f32_16x16x32_bf16 v[32:35], v[184:187], v[200:203], v[32:35]
	v_mfma_f32_16x16x32_bf16 v[20:23], v[176:179], v[208:211], v[20:23]
	v_mfma_f32_16x16x32_bf16 v[16:19], v[184:187], v[208:211], v[16:19]
	v_mfma_f32_16x16x32_bf16 v[4:7], v[176:179], v[216:219], v[4:7]
	v_mfma_f32_16x16x32_bf16 v[0:3], v[184:187], v[216:219], v[0:3]
	s_setprio 0
	s_barrier
	s_add_i32 s67, s67, 2
	s_add_u32 s46, s46, 0x100
	s_addc_u32 s47, s47, 0
	s_add_u32 s65, s65, 0x100
	s_addc_u32 s66, s66, 0
	s_cmp_gt_u32 s67, 13
	s_cbranch_scc0 .LBB0_1246
	s_and_b64 vcc, exec, s[16:17]
	s_cbranch_vccz .LBB0_1249
	s_barrier

.LBB0_1342:
	ds_read_b128 v[146:149], v154
	ds_read_b128 v[158:161], v154 offset:1024
	ds_read_b128 v[162:165], v154 offset:2048
	ds_read_b128 v[166:169], v154 offset:3072
	ds_read_b128 v[170:173], v155
	ds_read_b128 v[174:177], v155 offset:1024
	ds_read_b128 v[178:181], v155 offset:2048
	ds_read_b128 v[182:185], v155 offset:3072
	s_add_u32 s23, s40, 0xfffc0080
	s_addc_u32 s33, s41, -1
	s_cmp_eq_u32 s67, 12
	s_cselect_b32 s45, s19, s33
	s_cselect_b32 s44, s20, s23
	s_cselect_b32 s43, s17, s66
	s_cselect_b32 s42, s21, s65
	v_lshl_add_u64 v[218:219], s[40:41], 0, v[138:139]
	s_add_i32 m0, s52, 0xc000
	ds_read_b128 v[186:189], v156
	ds_read_b128 v[190:193], v156 offset:1024
	ds_read_b128 v[194:197], v156 offset:2048
	ds_read_b128 v[198:201], v156 offset:3072
	ds_read_b128 v[202:205], v156 offset:4096
	ds_read_b128 v[206:209], v156 offset:5120
	ds_read_b128 v[210:213], v156 offset:6144
	ds_read_b128 v[214:217], v156 offset:7168
	global_load_lds_dwordx4 v[218:219], off
	v_lshl_add_u64 v[218:219], s[40:41], 0, v[140:141]
	s_add_i32 m0, s52, 0xe000
	s_nop 0
	global_load_lds_dwordx4 v[218:219], off
	s_waitcnt vmcnt(8)
	s_waitcnt lgkmcnt(0)
	s_barrier
	s_setprio 1
	v_mfma_f32_16x16x32_bf16 v[116:119], v[146:149], v[186:189], v[116:119]
	v_mfma_f32_16x16x32_bf16 v[112:115], v[162:165], v[186:189], v[112:115]
	v_mfma_f32_16x16x32_bf16 v[100:103], v[146:149], v[194:197], v[100:103]
	v_mfma_f32_16x16x32_bf16 v[96:99], v[162:165], v[194:197], v[96:99]
	v_mfma_f32_16x16x32_bf16 v[84:87], v[146:149], v[202:205], v[84:87]
	v_mfma_f32_16x16x32_bf16 v[80:83], v[162:165], v[202:205], v[80:83]
	v_mfma_f32_16x16x32_bf16 v[72:75], v[146:149], v[210:213], v[72:75]
	v_mfma_f32_16x16x32_bf16 v[64:67], v[162:165], v[210:213], v[64:67]
	v_mfma_f32_16x16x32_bf16 v[116:119], v[158:161], v[190:193], v[116:119]
	v_mfma_f32_16x16x32_bf16 v[112:115], v[166:169], v[190:193], v[112:115]
	v_mfma_f32_16x16x32_bf16 v[100:103], v[158:161], v[198:201], v[100:103]
	v_mfma_f32_16x16x32_bf16 v[96:99], v[166:169], v[198:201], v[96:99]
	v_mfma_f32_16x16x32_bf16 v[84:87], v[158:161], v[206:209], v[84:87]
	v_mfma_f32_16x16x32_bf16 v[80:83], v[166:169], v[206:209], v[80:83]
	v_mfma_f32_16x16x32_bf16 v[72:75], v[158:161], v[214:217], v[72:75]
	v_mfma_f32_16x16x32_bf16 v[64:67], v[166:169], v[214:217], v[64:67]
	v_mfma_f32_16x16x32_bf16 v[124:127], v[170:173], v[186:189], v[124:127]
	v_mfma_f32_16x16x32_bf16 v[120:123], v[178:181], v[186:189], v[120:123]
	v_mfma_f32_16x16x32_bf16 v[108:111], v[170:173], v[194:197], v[108:111]
	v_mfma_f32_16x16x32_bf16 v[104:107], v[178:181], v[194:197], v[104:107]
	v_mfma_f32_16x16x32_bf16 v[92:95], v[170:173], v[202:205], v[92:95]
	v_mfma_f32_16x16x32_bf16 v[88:91], v[178:181], v[202:205], v[88:91]
	v_mfma_f32_16x16x32_bf16 v[76:79], v[170:173], v[210:213], v[76:79]
	v_mfma_f32_16x16x32_bf16 v[68:71], v[178:181], v[210:213], v[68:71]
	v_mfma_f32_16x16x32_bf16 v[124:127], v[174:177], v[190:193], v[124:127]
	v_mfma_f32_16x16x32_bf16 v[120:123], v[182:185], v[190:193], v[120:123]
	v_mfma_f32_16x16x32_bf16 v[108:111], v[174:177], v[198:201], v[108:111]
	v_mfma_f32_16x16x32_bf16 v[104:107], v[182:185], v[198:201], v[104:107]
	v_mfma_f32_16x16x32_bf16 v[92:95], v[174:177], v[206:209], v[92:95]
	v_mfma_f32_16x16x32_bf16 v[88:91], v[182:185], v[206:209], v[88:91]
	v_mfma_f32_16x16x32_bf16 v[76:79], v[174:177], v[214:217], v[76:79]
	v_mfma_f32_16x16x32_bf16 v[68:71], v[182:185], v[214:217], v[68:71]
	s_setprio 0
	s_barrier
	s_add_i32 s23, s61, s50
	v_lshl_add_u64 v[218:219], s[42:43], 0, v[132:133]
	s_mov_b32 m0, s23
	ds_read_b128 v[186:189], v156 offset:16384
	ds_read_b128 v[190:193], v156 offset:17408
	ds_read_b128 v[194:197], v156 offset:18432
	ds_read_b128 v[198:201], v156 offset:19456
	ds_read_b128 v[202:205], v156 offset:20480
	ds_read_b128 v[206:209], v156 offset:21504
	ds_read_b128 v[210:213], v156 offset:22528
	ds_read_b128 v[214:217], v156 offset:23552
	global_load_lds_dwordx4 v[218:219], off
	s_add_i32 m0, s23, 0x2000
	s_add_u32 s68, s42, 0x40000
	v_lshl_add_u64 v[220:221], s[42:43], 0, v[136:137]
	s_addc_u32 s69, s43, 0
	s_add_i32 s23, s62, s50
	global_load_lds_dwordx4 v[220:221], off
	v_lshl_add_u64 v[222:223], s[68:69], 0, v[132:133]
	s_mov_b32 m0, s23
	v_lshl_add_u64 v[224:225], s[44:45], 0, v[134:135]
	global_load_lds_dwordx4 v[222:223], off
	v_lshl_add_u64 v[222:223], s[68:69], 0, v[136:137]
	s_add_i32 m0, s23, 0x2000
	s_nop 0
	global_load_lds_dwordx4 v[222:223], off
	v_lshl_add_u64 v[222:223], s[44:45], 0, v[130:131]
	s_mov_b32 m0, s52
	s_nop 0
	global_load_lds_dwordx4 v[222:223], off
	s_mov_b32 m0, s53
	s_nop 0
	global_load_lds_dwordx4 v[224:225], off
	s_waitcnt vmcnt(8)
	s_waitcnt lgkmcnt(0)
	s_barrier
	s_setprio 1
	v_mfma_f32_16x16x32_bf16 v[56:59], v[146:149], v[186:189], v[56:59]
	v_mfma_f32_16x16x32_bf16 v[48:51], v[162:165], v[186:189], v[48:51]
	v_mfma_f32_16x16x32_bf16 v[40:43], v[146:149], v[194:197], v[40:43]
	v_mfma_f32_16x16x32_bf16 v[32:35], v[162:165], v[194:197], v[32:35]
	v_mfma_f32_16x16x32_bf16 v[24:27], v[146:149], v[202:205], v[24:27]
	v_mfma_f32_16x16x32_bf16 v[16:19], v[162:165], v[202:205], v[16:19]
	v_mfma_f32_16x16x32_bf16 v[8:11], v[146:149], v[210:213], v[8:11]
	v_mfma_f32_16x16x32_bf16 v[0:3], v[162:165], v[210:213], v[0:3]
	v_mfma_f32_16x16x32_bf16 v[56:59], v[158:161], v[190:193], v[56:59]
	v_mfma_f32_16x16x32_bf16 v[48:51], v[166:169], v[190:193], v[48:51]
	v_mfma_f32_16x16x32_bf16 v[40:43], v[158:161], v[198:201], v[40:43]
	v_mfma_f32_16x16x32_bf16 v[32:35], v[166:169], v[198:201], v[32:35]
	v_mfma_f32_16x16x32_bf16 v[24:27], v[158:161], v[206:209], v[24:27]
	v_mfma_f32_16x16x32_bf16 v[16:19], v[166:169], v[206:209], v[16:19]
	v_mfma_f32_16x16x32_bf16 v[8:11], v[158:161], v[214:217], v[8:11]
	v_mfma_f32_16x16x32_bf16 v[0:3], v[166:169], v[214:217], v[0:3]
	v_mfma_f32_16x16x32_bf16 v[60:63], v[170:173], v[186:189], v[60:63]
	v_mfma_f32_16x16x32_bf16 v[52:55], v[178:181], v[186:189], v[52:55]
	v_mfma_f32_16x16x32_bf16 v[44:47], v[170:173], v[194:197], v[44:47]
	v_mfma_f32_16x16x32_bf16 v[36:39], v[178:181], v[194:197], v[36:39]
	v_mfma_f32_16x16x32_bf16 v[28:31], v[170:173], v[202:205], v[28:31]
	v_mfma_f32_16x16x32_bf16 v[20:23], v[178:181], v[202:205], v[20:23]
	v_mfma_f32_16x16x32_bf16 v[12:15], v[170:173], v[210:213], v[12:15]
	v_mfma_f32_16x16x32_bf16 v[4:7], v[178:181], v[210:213], v[4:7]
	v_mfma_f32_16x16x32_bf16 v[60:63], v[174:177], v[190:193], v[60:63]
	v_mfma_f32_16x16x32_bf16 v[52:55], v[182:185], v[190:193], v[52:55]
	v_mfma_f32_16x16x32_bf16 v[44:47], v[174:177], v[198:201], v[44:47]
	v_mfma_f32_16x16x32_bf16 v[36:39], v[182:185], v[198:201], v[36:39]
	v_mfma_f32_16x16x32_bf16 v[28:31], v[174:177], v[206:209], v[28:31]
	v_mfma_f32_16x16x32_bf16 v[20:23], v[182:185], v[206:209], v[20:23]
	v_mfma_f32_16x16x32_bf16 v[12:15], v[174:177], v[214:217], v[12:15]
	v_mfma_f32_16x16x32_bf16 v[4:7], v[182:185], v[214:217], v[4:7]
	s_setprio 0
	s_barrier
	s_add_i32 s23, 0, 0x18000
	s_add_i32 s33, 0, 0x1c000
	v_add_u32_e32 v166, s23, v152
	v_add_u32_e32 v182, s33, v152
	ds_read_b128 v[146:149], v166
	ds_read_b128 v[158:161], v166 offset:1024
	ds_read_b128 v[162:165], v166 offset:2048
	ds_read_b128 v[166:169], v166 offset:3072
	ds_read_b128 v[170:173], v182
	ds_read_b128 v[174:177], v182 offset:1024
	ds_read_b128 v[178:181], v182 offset:2048
	ds_read_b128 v[182:185], v182 offset:3072
	s_add_u32 s44, s44, 0x40000
	s_addc_u32 s45, s45, 0
	s_mov_b32 m0, s54
	v_lshl_add_u64 v[226:227], s[44:45], 0, v[130:131]
	ds_read_b128 v[186:189], v156 offset:32768
	ds_read_b128 v[190:193], v156 offset:33792
	ds_read_b128 v[194:197], v156 offset:34816
	ds_read_b128 v[198:201], v156 offset:35840
	ds_read_b128 v[202:205], v156 offset:36864
	ds_read_b128 v[206:209], v156 offset:37888
	ds_read_b128 v[210:213], v156 offset:38912
	ds_read_b128 v[214:217], v156 offset:39936
	global_load_lds_dwordx4 v[226:227], off
	v_lshl_add_u64 v[226:227], s[44:45], 0, v[134:135]
	s_mov_b32 m0, s55
	s_nop 0
	global_load_lds_dwordx4 v[226:227], off
	s_waitcnt vmcnt(8)
	s_waitcnt lgkmcnt(0)
	s_barrier
	s_setprio 1
	v_mfma_f32_16x16x32_bf16 v[116:119], v[146:149], v[186:189], v[116:119]
	v_mfma_f32_16x16x32_bf16 v[112:115], v[162:165], v[186:189], v[112:115]
	v_mfma_f32_16x16x32_bf16 v[100:103], v[146:149], v[194:197], v[100:103]
	v_mfma_f32_16x16x32_bf16 v[96:99], v[162:165], v[194:197], v[96:99]
	v_mfma_f32_16x16x32_bf16 v[84:87], v[146:149], v[202:205], v[84:87]
	v_mfma_f32_16x16x32_bf16 v[80:83], v[162:165], v[202:205], v[80:83]
	v_mfma_f32_16x16x32_bf16 v[72:75], v[146:149], v[210:213], v[72:75]
	v_mfma_f32_16x16x32_bf16 v[64:67], v[162:165], v[210:213], v[64:67]
	v_mfma_f32_16x16x32_bf16 v[116:119], v[158:161], v[190:193], v[116:119]
	v_mfma_f32_16x16x32_bf16 v[112:115], v[166:169], v[190:193], v[112:115]
	v_mfma_f32_16x16x32_bf16 v[100:103], v[158:161], v[198:201], v[100:103]
	v_mfma_f32_16x16x32_bf16 v[96:99], v[166:169], v[198:201], v[96:99]
	v_mfma_f32_16x16x32_bf16 v[84:87], v[158:161], v[206:209], v[84:87]
	v_mfma_f32_16x16x32_bf16 v[80:83], v[166:169], v[206:209], v[80:83]
	v_mfma_f32_16x16x32_bf16 v[72:75], v[158:161], v[214:217], v[72:75]
	v_mfma_f32_16x16x32_bf16 v[64:67], v[166:169], v[214:217], v[64:67]
	v_mfma_f32_16x16x32_bf16 v[124:127], v[170:173], v[186:189], v[124:127]
	v_mfma_f32_16x16x32_bf16 v[120:123], v[178:181], v[186:189], v[120:123]
	v_mfma_f32_16x16x32_bf16 v[108:111], v[170:173], v[194:197], v[108:111]
	v_mfma_f32_16x16x32_bf16 v[104:107], v[178:181], v[194:197], v[104:107]
	v_mfma_f32_16x16x32_bf16 v[92:95], v[170:173], v[202:205], v[92:95]
	v_mfma_f32_16x16x32_bf16 v[88:91], v[178:181], v[202:205], v[88:91]
	v_mfma_f32_16x16x32_bf16 v[76:79], v[170:173], v[210:213], v[76:79]
	v_mfma_f32_16x16x32_bf16 v[68:71], v[178:181], v[210:213], v[68:71]
	v_mfma_f32_16x16x32_bf16 v[124:127], v[174:177], v[190:193], v[124:127]
	v_mfma_f32_16x16x32_bf16 v[120:123], v[182:185], v[190:193], v[120:123]
	v_mfma_f32_16x16x32_bf16 v[108:111], v[174:177], v[198:201], v[108:111]
	v_mfma_f32_16x16x32_bf16 v[104:107], v[182:185], v[198:201], v[104:107]
	v_mfma_f32_16x16x32_bf16 v[92:95], v[174:177], v[206:209], v[92:95]
	v_mfma_f32_16x16x32_bf16 v[88:91], v[182:185], v[206:209], v[88:91]
	v_mfma_f32_16x16x32_bf16 v[76:79], v[174:177], v[214:217], v[76:79]
	v_mfma_f32_16x16x32_bf16 v[68:71], v[182:185], v[214:217], v[68:71]
	s_setprio 0
	s_barrier
	s_add_i32 s23, s23, s50
	v_lshl_add_u64 v[218:219], v[218:219], 0, s[12:13]
	s_mov_b32 m0, s23
	ds_read_b128 v[186:189], v156 offset:49152
	ds_read_b128 v[190:193], v156 offset:50176
	ds_read_b128 v[194:197], v156 offset:51200
	ds_read_b128 v[198:201], v156 offset:52224
	ds_read_b128 v[202:205], v156 offset:53248
	ds_read_b128 v[206:209], v156 offset:54272
	ds_read_b128 v[210:213], v156 offset:55296
	ds_read_b128 v[214:217], v156 offset:56320
	global_load_lds_dwordx4 v[218:219], off
	s_add_i32 m0, s23, 0x2000
	s_add_u32 s42, s42, 0x40080
	v_lshl_add_u64 v[218:219], v[220:221], 0, s[12:13]
	s_addc_u32 s43, s43, 0
	s_add_i32 s23, s33, s50
	global_load_lds_dwordx4 v[218:219], off
	v_lshl_add_u64 v[218:219], s[42:43], 0, v[132:133]
	s_mov_b32 m0, s23
	s_nop 0
	global_load_lds_dwordx4 v[218:219], off
	v_lshl_add_u64 v[218:219], s[42:43], 0, v[136:137]
	s_add_i32 m0, s23, 0x2000
	s_nop 0
	global_load_lds_dwordx4 v[218:219], off
	v_lshl_add_u64 v[218:219], v[222:223], 0, s[12:13]
	s_mov_b32 m0, s58
	s_nop 0
	global_load_lds_dwordx4 v[218:219], off
	v_lshl_add_u64 v[218:219], v[224:225], 0, s[12:13]
	s_mov_b32 m0, s59
	s_nop 0
	global_load_lds_dwordx4 v[218:219], off
	s_waitcnt vmcnt(8)
	s_waitcnt lgkmcnt(0)
	s_barrier
	s_setprio 1
	v_mfma_f32_16x16x32_bf16 v[56:59], v[146:149], v[186:189], v[56:59]
	v_mfma_f32_16x16x32_bf16 v[48:51], v[162:165], v[186:189], v[48:51]
	v_mfma_f32_16x16x32_bf16 v[40:43], v[146:149], v[194:197], v[40:43]
	v_mfma_f32_16x16x32_bf16 v[32:35], v[162:165], v[194:197], v[32:35]
	v_mfma_f32_16x16x32_bf16 v[24:27], v[146:149], v[202:205], v[24:27]
	v_mfma_f32_16x16x32_bf16 v[16:19], v[162:165], v[202:205], v[16:19]
	v_mfma_f32_16x16x32_bf16 v[8:11], v[146:149], v[210:213], v[8:11]
	v_mfma_f32_16x16x32_bf16 v[0:3], v[162:165], v[210:213], v[0:3]
	v_mfma_f32_16x16x32_bf16 v[56:59], v[158:161], v[190:193], v[56:59]
	v_mfma_f32_16x16x32_bf16 v[48:51], v[166:169], v[190:193], v[48:51]
	v_mfma_f32_16x16x32_bf16 v[40:43], v[158:161], v[198:201], v[40:43]
	v_mfma_f32_16x16x32_bf16 v[32:35], v[166:169], v[198:201], v[32:35]
	v_mfma_f32_16x16x32_bf16 v[24:27], v[158:161], v[206:209], v[24:27]
	v_mfma_f32_16x16x32_bf16 v[16:19], v[166:169], v[206:209], v[16:19]
	v_mfma_f32_16x16x32_bf16 v[8:11], v[158:161], v[214:217], v[8:11]
	v_mfma_f32_16x16x32_bf16 v[0:3], v[166:169], v[214:217], v[0:3]
	v_mfma_f32_16x16x32_bf16 v[60:63], v[170:173], v[186:189], v[60:63]
	v_mfma_f32_16x16x32_bf16 v[52:55], v[178:181], v[186:189], v[52:55]
	v_mfma_f32_16x16x32_bf16 v[44:47], v[170:173], v[194:197], v[44:47]
	v_mfma_f32_16x16x32_bf16 v[36:39], v[178:181], v[194:197], v[36:39]
	v_mfma_f32_16x16x32_bf16 v[28:31], v[170:173], v[202:205], v[28:31]
	v_mfma_f32_16x16x32_bf16 v[20:23], v[178:181], v[202:205], v[20:23]
	v_mfma_f32_16x16x32_bf16 v[12:15], v[170:173], v[210:213], v[12:15]
	v_mfma_f32_16x16x32_bf16 v[4:7], v[178:181], v[210:213], v[4:7]
	v_mfma_f32_16x16x32_bf16 v[60:63], v[174:177], v[190:193], v[60:63]
	v_mfma_f32_16x16x32_bf16 v[52:55], v[182:185], v[190:193], v[52:55]
	v_mfma_f32_16x16x32_bf16 v[44:47], v[174:177], v[198:201], v[44:47]
	v_mfma_f32_16x16x32_bf16 v[36:39], v[182:185], v[198:201], v[36:39]
	v_mfma_f32_16x16x32_bf16 v[28:31], v[174:177], v[206:209], v[28:31]
	v_mfma_f32_16x16x32_bf16 v[20:23], v[182:185], v[206:209], v[20:23]
	v_mfma_f32_16x16x32_bf16 v[12:15], v[174:177], v[214:217], v[12:15]
	v_mfma_f32_16x16x32_bf16 v[4:7], v[182:185], v[214:217], v[4:7]
	s_setprio 0
	s_barrier
	s_add_i32 s67, s67, 2
	s_add_u32 s40, s40, 0x100
	s_addc_u32 s41, s41, 0
	s_add_u32 s65, s65, 0x100
	s_addc_u32 s66, s66, 0
	s_cmp_gt_u32 s67, 13
	s_cbranch_scc0 .LBB0_1342
	s_and_b64 vcc, exec, s[14:15]
	s_cbranch_vccz .LBB0_1345
	s_barrier

.LBB0_1424:
	ds_read_b128 v[146:149], v156
	ds_read_b128 v[160:163], v156 offset:1024
	ds_read_b128 v[164:167], v156 offset:2048
	ds_read_b128 v[168:171], v156 offset:3072
	ds_read_b128 v[172:175], v157
	ds_read_b128 v[176:179], v157 offset:1024
	ds_read_b128 v[180:183], v157 offset:2048
	ds_read_b128 v[184:187], v157 offset:3072
	s_add_u32 s23, s38, 0xfff50080
	s_addc_u32 s33, s39, -1
	s_cmp_eq_u32 s65, 40
	s_cselect_b32 s43, s1, s33
	s_cselect_b32 s42, s0, s23
	s_cselect_b32 s41, s37, s64
	s_cselect_b32 s40, s36, s63
	v_lshl_add_u64 v[220:221], s[38:39], 0, v[138:139]
	s_add_i32 m0, s49, 0xc000
	ds_read_b128 v[188:191], v158
	ds_read_b128 v[192:195], v158 offset:1024
	ds_read_b128 v[196:199], v158 offset:2048
	ds_read_b128 v[200:203], v158 offset:3072
	ds_read_b128 v[204:207], v158 offset:4096
	ds_read_b128 v[208:211], v158 offset:5120
	ds_read_b128 v[212:215], v158 offset:6144
	ds_read_b128 v[216:219], v158 offset:7168
	global_load_lds_dwordx4 v[220:221], off
	v_lshl_add_u64 v[220:221], s[38:39], 0, v[140:141]
	s_add_i32 m0, s49, 0xe000
	s_nop 0
	global_load_lds_dwordx4 v[220:221], off
	s_waitcnt vmcnt(8)
	s_waitcnt lgkmcnt(0)
	s_barrier
	s_setprio 1
	v_mfma_f32_16x16x32_bf16 v[124:127], v[146:149], v[188:191], v[124:127]
	v_mfma_f32_16x16x32_bf16 v[120:123], v[164:167], v[188:191], v[120:123]
	v_mfma_f32_16x16x32_bf16 v[108:111], v[146:149], v[196:199], v[108:111]
	v_mfma_f32_16x16x32_bf16 v[104:107], v[164:167], v[196:199], v[104:107]
	v_mfma_f32_16x16x32_bf16 v[92:95], v[146:149], v[204:207], v[92:95]
	v_mfma_f32_16x16x32_bf16 v[88:91], v[164:167], v[204:207], v[88:91]
	v_mfma_f32_16x16x32_bf16 v[76:79], v[146:149], v[212:215], v[76:79]
	v_mfma_f32_16x16x32_bf16 v[72:75], v[164:167], v[212:215], v[72:75]
	v_mfma_f32_16x16x32_bf16 v[124:127], v[160:163], v[192:195], v[124:127]
	v_mfma_f32_16x16x32_bf16 v[120:123], v[168:171], v[192:195], v[120:123]
	v_mfma_f32_16x16x32_bf16 v[108:111], v[160:163], v[200:203], v[108:111]
	v_mfma_f32_16x16x32_bf16 v[104:107], v[168:171], v[200:203], v[104:107]
	v_mfma_f32_16x16x32_bf16 v[92:95], v[160:163], v[208:211], v[92:95]
	v_mfma_f32_16x16x32_bf16 v[88:91], v[168:171], v[208:211], v[88:91]
	v_mfma_f32_16x16x32_bf16 v[76:79], v[160:163], v[216:219], v[76:79]
	v_mfma_f32_16x16x32_bf16 v[72:75], v[168:171], v[216:219], v[72:75]
	v_mfma_f32_16x16x32_bf16 v[116:119], v[172:175], v[188:191], v[116:119]
	v_mfma_f32_16x16x32_bf16 v[112:115], v[180:183], v[188:191], v[112:115]
	v_mfma_f32_16x16x32_bf16 v[100:103], v[172:175], v[196:199], v[100:103]
	v_mfma_f32_16x16x32_bf16 v[96:99], v[180:183], v[196:199], v[96:99]
	v_mfma_f32_16x16x32_bf16 v[84:87], v[172:175], v[204:207], v[84:87]
	v_mfma_f32_16x16x32_bf16 v[80:83], v[180:183], v[204:207], v[80:83]
	v_mfma_f32_16x16x32_bf16 v[68:71], v[172:175], v[212:215], v[68:71]
	v_mfma_f32_16x16x32_bf16 v[64:67], v[180:183], v[212:215], v[64:67]
	v_mfma_f32_16x16x32_bf16 v[116:119], v[176:179], v[192:195], v[116:119]
	v_mfma_f32_16x16x32_bf16 v[112:115], v[184:187], v[192:195], v[112:115]
	v_mfma_f32_16x16x32_bf16 v[100:103], v[176:179], v[200:203], v[100:103]
	v_mfma_f32_16x16x32_bf16 v[96:99], v[184:187], v[200:203], v[96:99]
	v_mfma_f32_16x16x32_bf16 v[84:87], v[176:179], v[208:211], v[84:87]
	v_mfma_f32_16x16x32_bf16 v[80:83], v[184:187], v[208:211], v[80:83]
	v_mfma_f32_16x16x32_bf16 v[68:71], v[176:179], v[216:219], v[68:71]
	v_mfma_f32_16x16x32_bf16 v[64:67], v[184:187], v[216:219], v[64:67]
	s_setprio 0
	s_barrier
	s_add_i32 s23, s59, s48
	v_lshl_add_u64 v[220:221], s[40:41], 0, v[132:133]
	s_mov_b32 m0, s23
	ds_read_b128 v[188:191], v158 offset:16384
	ds_read_b128 v[192:195], v158 offset:17408
	ds_read_b128 v[196:199], v158 offset:18432
	ds_read_b128 v[200:203], v158 offset:19456
	ds_read_b128 v[204:207], v158 offset:20480
	ds_read_b128 v[208:211], v158 offset:21504
	ds_read_b128 v[212:215], v158 offset:22528
	ds_read_b128 v[216:219], v158 offset:23552
	global_load_lds_dwordx4 v[220:221], off
	s_add_i32 m0, s23, 0x2000
	s_add_u32 s66, s40, 0xb0000
	v_lshl_add_u64 v[222:223], s[40:41], 0, v[136:137]
	s_addc_u32 s67, s41, 0
	s_add_i32 s23, s60, s48
	global_load_lds_dwordx4 v[222:223], off
	v_lshl_add_u64 v[224:225], s[66:67], 0, v[132:133]
	s_mov_b32 m0, s23
	v_lshl_add_u64 v[226:227], s[42:43], 0, v[134:135]
	global_load_lds_dwordx4 v[224:225], off
	v_lshl_add_u64 v[224:225], s[66:67], 0, v[136:137]
	s_add_i32 m0, s23, 0x2000
	s_nop 0
	global_load_lds_dwordx4 v[224:225], off
	v_lshl_add_u64 v[224:225], s[42:43], 0, v[130:131]
	s_mov_b32 m0, s49
	s_nop 0
	global_load_lds_dwordx4 v[224:225], off
	s_mov_b32 m0, s50
	s_nop 0
	global_load_lds_dwordx4 v[226:227], off
	s_waitcnt vmcnt(8)
	s_waitcnt lgkmcnt(0)
	s_barrier
	s_setprio 1
	v_mfma_f32_16x16x32_bf16 v[60:63], v[146:149], v[188:191], v[60:63]
	v_mfma_f32_16x16x32_bf16 v[56:59], v[164:167], v[188:191], v[56:59]
	v_mfma_f32_16x16x32_bf16 v[44:47], v[146:149], v[196:199], v[44:47]
	v_mfma_f32_16x16x32_bf16 v[40:43], v[164:167], v[196:199], v[40:43]
	v_mfma_f32_16x16x32_bf16 v[28:31], v[146:149], v[204:207], v[28:31]
	v_mfma_f32_16x16x32_bf16 v[24:27], v[164:167], v[204:207], v[24:27]
	v_mfma_f32_16x16x32_bf16 v[12:15], v[146:149], v[212:215], v[12:15]
	v_mfma_f32_16x16x32_bf16 v[8:11], v[164:167], v[212:215], v[8:11]
	v_mfma_f32_16x16x32_bf16 v[60:63], v[160:163], v[192:195], v[60:63]
	v_mfma_f32_16x16x32_bf16 v[56:59], v[168:171], v[192:195], v[56:59]
	v_mfma_f32_16x16x32_bf16 v[44:47], v[160:163], v[200:203], v[44:47]
	v_mfma_f32_16x16x32_bf16 v[40:43], v[168:171], v[200:203], v[40:43]
	v_mfma_f32_16x16x32_bf16 v[28:31], v[160:163], v[208:211], v[28:31]
	v_mfma_f32_16x16x32_bf16 v[24:27], v[168:171], v[208:211], v[24:27]
	v_mfma_f32_16x16x32_bf16 v[12:15], v[160:163], v[216:219], v[12:15]
	v_mfma_f32_16x16x32_bf16 v[8:11], v[168:171], v[216:219], v[8:11]
	v_mfma_f32_16x16x32_bf16 v[52:55], v[172:175], v[188:191], v[52:55]
	v_mfma_f32_16x16x32_bf16 v[48:51], v[180:183], v[188:191], v[48:51]
	v_mfma_f32_16x16x32_bf16 v[36:39], v[172:175], v[196:199], v[36:39]
	v_mfma_f32_16x16x32_bf16 v[32:35], v[180:183], v[196:199], v[32:35]
	v_mfma_f32_16x16x32_bf16 v[20:23], v[172:175], v[204:207], v[20:23]
	v_mfma_f32_16x16x32_bf16 v[16:19], v[180:183], v[204:207], v[16:19]
	v_mfma_f32_16x16x32_bf16 v[4:7], v[172:175], v[212:215], v[4:7]
	v_mfma_f32_16x16x32_bf16 v[0:3], v[180:183], v[212:215], v[0:3]
	v_mfma_f32_16x16x32_bf16 v[52:55], v[176:179], v[192:195], v[52:55]
	v_mfma_f32_16x16x32_bf16 v[48:51], v[184:187], v[192:195], v[48:51]
	v_mfma_f32_16x16x32_bf16 v[36:39], v[176:179], v[200:203], v[36:39]
	v_mfma_f32_16x16x32_bf16 v[32:35], v[184:187], v[200:203], v[32:35]
	v_mfma_f32_16x16x32_bf16 v[20:23], v[176:179], v[208:211], v[20:23]
	v_mfma_f32_16x16x32_bf16 v[16:19], v[184:187], v[208:211], v[16:19]
	v_mfma_f32_16x16x32_bf16 v[4:7], v[176:179], v[216:219], v[4:7]
	v_mfma_f32_16x16x32_bf16 v[0:3], v[184:187], v[216:219], v[0:3]
	s_setprio 0
	s_barrier
	s_add_i32 s23, 0, 0x18000
	s_add_i32 s33, 0, 0x1c000
	v_add_u32_e32 v168, s23, v154
	v_add_u32_e32 v184, s33, v154
	ds_read_b128 v[146:149], v168
	ds_read_b128 v[160:163], v168 offset:1024
	ds_read_b128 v[164:167], v168 offset:2048
	ds_read_b128 v[168:171], v168 offset:3072
	ds_read_b128 v[172:175], v184
	ds_read_b128 v[176:179], v184 offset:1024
	ds_read_b128 v[180:183], v184 offset:2048
	ds_read_b128 v[184:187], v184 offset:3072
	s_add_u32 s42, s42, 0xb0000
	s_addc_u32 s43, s43, 0
	s_mov_b32 m0, s51
	v_lshl_add_u64 v[228:229], s[42:43], 0, v[130:131]
	ds_read_b128 v[188:191], v158 offset:32768
	ds_read_b128 v[192:195], v158 offset:33792
	ds_read_b128 v[196:199], v158 offset:34816
	ds_read_b128 v[200:203], v158 offset:35840
	ds_read_b128 v[204:207], v158 offset:36864
	ds_read_b128 v[208:211], v158 offset:37888
	ds_read_b128 v[212:215], v158 offset:38912
	ds_read_b128 v[216:219], v158 offset:39936
	global_load_lds_dwordx4 v[228:229], off
	v_lshl_add_u64 v[228:229], s[42:43], 0, v[134:135]
	s_mov_b32 m0, s52
	s_nop 0
	global_load_lds_dwordx4 v[228:229], off
	s_waitcnt vmcnt(8)
	s_waitcnt lgkmcnt(0)
	s_barrier
	s_setprio 1
	v_mfma_f32_16x16x32_bf16 v[124:127], v[146:149], v[188:191], v[124:127]
	v_mfma_f32_16x16x32_bf16 v[120:123], v[164:167], v[188:191], v[120:123]
	v_mfma_f32_16x16x32_bf16 v[108:111], v[146:149], v[196:199], v[108:111]
	v_mfma_f32_16x16x32_bf16 v[104:107], v[164:167], v[196:199], v[104:107]
	v_mfma_f32_16x16x32_bf16 v[92:95], v[146:149], v[204:207], v[92:95]
	v_mfma_f32_16x16x32_bf16 v[88:91], v[164:167], v[204:207], v[88:91]
	v_mfma_f32_16x16x32_bf16 v[76:79], v[146:149], v[212:215], v[76:79]
	v_mfma_f32_16x16x32_bf16 v[72:75], v[164:167], v[212:215], v[72:75]
	v_mfma_f32_16x16x32_bf16 v[124:127], v[160:163], v[192:195], v[124:127]
	v_mfma_f32_16x16x32_bf16 v[120:123], v[168:171], v[192:195], v[120:123]
	v_mfma_f32_16x16x32_bf16 v[108:111], v[160:163], v[200:203], v[108:111]
	v_mfma_f32_16x16x32_bf16 v[104:107], v[168:171], v[200:203], v[104:107]
	v_mfma_f32_16x16x32_bf16 v[92:95], v[160:163], v[208:211], v[92:95]
	v_mfma_f32_16x16x32_bf16 v[88:91], v[168:171], v[208:211], v[88:91]
	v_mfma_f32_16x16x32_bf16 v[76:79], v[160:163], v[216:219], v[76:79]
	v_mfma_f32_16x16x32_bf16 v[72:75], v[168:171], v[216:219], v[72:75]
	v_mfma_f32_16x16x32_bf16 v[116:119], v[172:175], v[188:191], v[116:119]
	v_mfma_f32_16x16x32_bf16 v[112:115], v[180:183], v[188:191], v[112:115]
	v_mfma_f32_16x16x32_bf16 v[100:103], v[172:175], v[196:199], v[100:103]
	v_mfma_f32_16x16x32_bf16 v[96:99], v[180:183], v[196:199], v[96:99]
	v_mfma_f32_16x16x32_bf16 v[84:87], v[172:175], v[204:207], v[84:87]
	v_mfma_f32_16x16x32_bf16 v[80:83], v[180:183], v[204:207], v[80:83]
	v_mfma_f32_16x16x32_bf16 v[68:71], v[172:175], v[212:215], v[68:71]
	v_mfma_f32_16x16x32_bf16 v[64:67], v[180:183], v[212:215], v[64:67]
	v_mfma_f32_16x16x32_bf16 v[116:119], v[176:179], v[192:195], v[116:119]
	v_mfma_f32_16x16x32_bf16 v[112:115], v[184:187], v[192:195], v[112:115]
	v_mfma_f32_16x16x32_bf16 v[100:103], v[176:179], v[200:203], v[100:103]
	v_mfma_f32_16x16x32_bf16 v[96:99], v[184:187], v[200:203], v[96:99]
	v_mfma_f32_16x16x32_bf16 v[84:87], v[176:179], v[208:211], v[84:87]
	v_mfma_f32_16x16x32_bf16 v[80:83], v[184:187], v[208:211], v[80:83]
	v_mfma_f32_16x16x32_bf16 v[68:71], v[176:179], v[216:219], v[68:71]
	v_mfma_f32_16x16x32_bf16 v[64:67], v[184:187], v[216:219], v[64:67]
	s_setprio 0
	s_barrier
	s_add_i32 s23, s23, s48
	v_lshl_add_u64 v[220:221], v[220:221], 0, s[16:17]
	s_mov_b32 m0, s23
	ds_read_b128 v[188:191], v158 offset:49152
	ds_read_b128 v[192:195], v158 offset:50176
	ds_read_b128 v[196:199], v158 offset:51200
	ds_read_b128 v[200:203], v158 offset:52224
	ds_read_b128 v[204:207], v158 offset:53248
	ds_read_b128 v[208:211], v158 offset:54272
	ds_read_b128 v[212:215], v158 offset:55296
	ds_read_b128 v[216:219], v158 offset:56320
	global_load_lds_dwordx4 v[220:221], off
	s_add_i32 m0, s23, 0x2000
	s_add_u32 s40, s40, 0xb0080
	v_lshl_add_u64 v[220:221], v[222:223], 0, s[16:17]
	s_addc_u32 s41, s41, 0
	s_add_i32 s23, s33, s48
	global_load_lds_dwordx4 v[220:221], off
	v_lshl_add_u64 v[220:221], s[40:41], 0, v[132:133]
	s_mov_b32 m0, s23
	s_nop 0
	global_load_lds_dwordx4 v[220:221], off
	v_lshl_add_u64 v[220:221], s[40:41], 0, v[136:137]
	s_add_i32 m0, s23, 0x2000
	s_nop 0
	global_load_lds_dwordx4 v[220:221], off
	v_lshl_add_u64 v[220:221], v[224:225], 0, s[16:17]
	s_mov_b32 m0, s56
	s_nop 0
	global_load_lds_dwordx4 v[220:221], off
	v_lshl_add_u64 v[220:221], v[226:227], 0, s[16:17]
	s_mov_b32 m0, s57
	s_nop 0
	global_load_lds_dwordx4 v[220:221], off
	s_waitcnt vmcnt(8)
	s_waitcnt lgkmcnt(0)
	s_barrier
	s_setprio 1
	v_mfma_f32_16x16x32_bf16 v[60:63], v[146:149], v[188:191], v[60:63]
	v_mfma_f32_16x16x32_bf16 v[56:59], v[164:167], v[188:191], v[56:59]
	v_mfma_f32_16x16x32_bf16 v[44:47], v[146:149], v[196:199], v[44:47]
	v_mfma_f32_16x16x32_bf16 v[40:43], v[164:167], v[196:199], v[40:43]
	v_mfma_f32_16x16x32_bf16 v[28:31], v[146:149], v[204:207], v[28:31]
	v_mfma_f32_16x16x32_bf16 v[24:27], v[164:167], v[204:207], v[24:27]
	v_mfma_f32_16x16x32_bf16 v[12:15], v[146:149], v[212:215], v[12:15]
	v_mfma_f32_16x16x32_bf16 v[8:11], v[164:167], v[212:215], v[8:11]
	v_mfma_f32_16x16x32_bf16 v[60:63], v[160:163], v[192:195], v[60:63]
	v_mfma_f32_16x16x32_bf16 v[56:59], v[168:171], v[192:195], v[56:59]
	v_mfma_f32_16x16x32_bf16 v[44:47], v[160:163], v[200:203], v[44:47]
	v_mfma_f32_16x16x32_bf16 v[40:43], v[168:171], v[200:203], v[40:43]
	v_mfma_f32_16x16x32_bf16 v[28:31], v[160:163], v[208:211], v[28:31]
	v_mfma_f32_16x16x32_bf16 v[24:27], v[168:171], v[208:211], v[24:27]
	v_mfma_f32_16x16x32_bf16 v[12:15], v[160:163], v[216:219], v[12:15]
	v_mfma_f32_16x16x32_bf16 v[8:11], v[168:171], v[216:219], v[8:11]
	v_mfma_f32_16x16x32_bf16 v[52:55], v[172:175], v[188:191], v[52:55]
	v_mfma_f32_16x16x32_bf16 v[48:51], v[180:183], v[188:191], v[48:51]
	v_mfma_f32_16x16x32_bf16 v[36:39], v[172:175], v[196:199], v[36:39]
	v_mfma_f32_16x16x32_bf16 v[32:35], v[180:183], v[196:199], v[32:35]
	v_mfma_f32_16x16x32_bf16 v[20:23], v[172:175], v[204:207], v[20:23]
	v_mfma_f32_16x16x32_bf16 v[16:19], v[180:183], v[204:207], v[16:19]
	v_mfma_f32_16x16x32_bf16 v[4:7], v[172:175], v[212:215], v[4:7]
	v_mfma_f32_16x16x32_bf16 v[0:3], v[180:183], v[212:215], v[0:3]
	v_mfma_f32_16x16x32_bf16 v[52:55], v[176:179], v[192:195], v[52:55]
	v_mfma_f32_16x16x32_bf16 v[48:51], v[184:187], v[192:195], v[48:51]
	v_mfma_f32_16x16x32_bf16 v[36:39], v[176:179], v[200:203], v[36:39]
	v_mfma_f32_16x16x32_bf16 v[32:35], v[184:187], v[200:203], v[32:35]
	v_mfma_f32_16x16x32_bf16 v[20:23], v[176:179], v[208:211], v[20:23]
	v_mfma_f32_16x16x32_bf16 v[16:19], v[184:187], v[208:211], v[16:19]
	v_mfma_f32_16x16x32_bf16 v[4:7], v[176:179], v[216:219], v[4:7]
	v_mfma_f32_16x16x32_bf16 v[0:3], v[184:187], v[216:219], v[0:3]
	s_setprio 0
	s_barrier
	s_add_i32 s65, s65, 2
	s_add_u32 s38, s38, 0x100
	s_addc_u32 s39, s39, 0
	s_add_u32 s63, s63, 0x100
	s_addc_u32 s64, s64, 0
	s_cmp_gt_u32 s65, 41
	s_cbranch_scc0 .LBB0_1424
	s_and_b64 vcc, exec, s[18:19]
	s_cbranch_vccz .LBB0_1427
	s_barrier
